# SwiGLU K-loops (P2,P9): setprio 0 and the four pointer adds moved past the back-edge barrier on the loop-back path, matching the other GEMM loops; on top of v34
# speedup vs baseline: 1.0012x; 1.0012x over previous
; #define PG8_STAGE(bufoff, gbase, voff) do { _Pragma("unroll") for (int _i = 0; _i < 2; ++_i) \
;         __builtin_amdgcn_global_load_lds((const unsigned*)((const char*)(gbase) + (voff)[_i]), (LAS unsigned*)(lds + (bufoff) + ldsw + _i * 8192), 16, 0, 0); } while (0)
; #define PG8_LDA(dst, b, h) do { _Pragma("unroll") for (int m = 0; m < 4; ++m) _Pragma("unroll") for (int k = 0; k < 2; ++k) dst[m][k] = *(const LAS bf16x8*)(lds + PG8_SA(b, h) + aoff + m * 2048 + k * 1024); } while (0)
; #define PG8_LDB(dst, b, h) do { _Pragma("unroll") for (int n = 0; n < 2; ++n) _Pragma("unroll") for (int k = 0; k < 2; ++k) dst[n][k] = *(const LAS bf16x8*)(lds + PG8_SB(b, h) + boff + n * 2048 + k * 1024); } while (0)
; #define PG8_MMA(ai, bj, At, Bt) do { __builtin_amdgcn_s_setprio(1); _Pragma("unroll") for (int m = 0; m < 4; ++m) _Pragma("unroll") for (int n = 0; n < 2; ++n) _Pragma("unroll") for (int k = 0; k < 2; ++k) \
;         acc[ai][bj][m][n] = __builtin_amdgcn_mfma_f32_16x16x32_bf16(Bt[n][k], At[m][k], acc[ai][bj][m][n], 0, 0, 0); __builtin_amdgcn_s_setprio(0); } while (0)
; #define PG8_WAIT_V(n) asm volatile("s_waitcnt vmcnt(" #n ")" ::: "memory")
; #define PG8_WAIT_L(n) asm volatile("s_waitcnt lgkmcnt(" #n ")" ::: "memory")
; #define PG8_BAR __builtin_amdgcn_s_barrier()
; #define PG8_SCHED __builtin_amdgcn_sched_barrier(0)
; template <class Epi, class Sched>
; __device__ __forceinline__ void gemm_phase(LAS unsigned char* lds, const Gemm g, const Sched& S, const Epi& E) {
;     ...
;             PG8_LDB(B0, 0, 0); PG8_SCHED; PG8_LDA(At, 0, 0); PG8_STAGE(PG8_SA(1, 1), a1 + hstep, voffA);
;             PG8_WAIT_L(8); PG8_BAR; PG8_WAIT_L(0); PG8_MMA(0, 0, At, B0); PG8_BAR; PG8_SCHED;
;             PG8_LDB(B1, 0, 1); PG8_STAGE(PG8_SB(0, 0), b2, voffB);
;             PG8_BAR; PG8_WAIT_L(0); PG8_MMA(0, 1, At, B1); PG8_BAR;
;             PG8_LDA(At, 0, 1); PG8_STAGE(PG8_SA(0, 0), a2, voffA);
;             PG8_BAR; PG8_WAIT_L(0); PG8_MMA(1, 0, At, B0); PG8_BAR; PG8_SCHED;
;             PG8_STAGE(PG8_SB(0, 1), b2 + hstep, voffB);
;             PG8_WAIT_V(6); PG8_BAR; PG8_MMA(1, 1, At, B1); PG8_BAR;
.LBB0_235:
	ds_read_b128 v[150:153], v147
	ds_read_b128 v[154:157], v147 offset:1024
	ds_read_b128 v[158:161], v147 offset:2048
	ds_read_b128 v[162:165], v147 offset:3072
	s_add_u32 s16, s14, 0xfffc0080
	s_addc_u32 s17, s15, -1
	s_cmp_eq_u32 s48, 12
	s_cselect_b32 s23, s7, s17
	s_cselect_b32 s22, s44, s16
	s_cselect_b32 s19, s5, s47
	s_cselect_b32 s18, s45, s46
	s_add_i32 m0, s13, 0xc000
	ds_read_b128 v[166:169], v148
	ds_read_b128 v[170:173], v148 offset:1024
	ds_read_b128 v[174:177], v148 offset:2048
	ds_read_b128 v[178:181], v148 offset:3072
	ds_read_b128 v[182:185], v148 offset:4096
	ds_read_b128 v[186:189], v148 offset:5120
	ds_read_b128 v[190:193], v148 offset:6144
	ds_read_b128 v[194:197], v148 offset:7168
	global_load_lds_dwordx4 v136, s[14:15]
	s_add_i32 m0, s13, 0xe000
	s_nop 0
	global_load_lds_dwordx4 v138, s[14:15]
	s_waitcnt lgkmcnt(8)
	s_waitcnt vmcnt(8)
	s_setprio 1
	s_barrier
	s_waitcnt lgkmcnt(0)
	v_mfma_f32_16x16x32_bf16 v[124:127], v[150:153], v[166:169], v[124:127]
	v_mfma_f32_16x16x32_bf16 v[116:119], v[158:161], v[166:169], v[116:119]
	v_mfma_f32_16x16x32_bf16 v[108:111], v[150:153], v[174:177], v[108:111]
	v_mfma_f32_16x16x32_bf16 v[100:103], v[158:161], v[174:177], v[100:103]
	v_mfma_f32_16x16x32_bf16 v[92:95], v[150:153], v[182:185], v[92:95]
	v_mfma_f32_16x16x32_bf16 v[84:87], v[158:161], v[182:185], v[84:87]
	v_mfma_f32_16x16x32_bf16 v[76:79], v[150:153], v[190:193], v[76:79]
	v_mfma_f32_16x16x32_bf16 v[68:71], v[158:161], v[190:193], v[68:71]
	v_mfma_f32_16x16x32_bf16 v[124:127], v[154:157], v[170:173], v[124:127]
	v_mfma_f32_16x16x32_bf16 v[116:119], v[162:165], v[170:173], v[116:119]
	v_mfma_f32_16x16x32_bf16 v[108:111], v[154:157], v[178:181], v[108:111]
	v_mfma_f32_16x16x32_bf16 v[100:103], v[162:165], v[178:181], v[100:103]
	v_mfma_f32_16x16x32_bf16 v[92:95], v[154:157], v[186:189], v[92:95]
	v_mfma_f32_16x16x32_bf16 v[84:87], v[162:165], v[186:189], v[84:87]
	v_mfma_f32_16x16x32_bf16 v[76:79], v[154:157], v[194:197], v[76:79]
	v_mfma_f32_16x16x32_bf16 v[68:71], v[162:165], v[194:197], v[68:71]
	s_barrier
	s_setprio 0
	s_add_i32 s16, s40, s25
	s_mov_b32 m0, s16
	ds_read_b128 v[202:205], v149
	ds_read_b128 v[206:209], v149 offset:1024
	ds_read_b128 v[210:213], v149 offset:2048
	ds_read_b128 v[214:217], v149 offset:3072
	global_load_lds_dwordx4 v132, s[18:19]
	s_add_i32 m0, s16, 0x2000
	s_nop 0
	global_load_lds_dwordx4 v128, s[18:19]
	s_waitcnt vmcnt(8)
	s_setprio 1
	s_barrier
	s_waitcnt lgkmcnt(0)
	v_mfma_f32_16x16x32_bf16 v[120:123], v[202:205], v[166:169], v[120:123]
	v_mfma_f32_16x16x32_bf16 v[112:115], v[210:213], v[166:169], v[112:115]
	v_mfma_f32_16x16x32_bf16 v[104:107], v[202:205], v[174:177], v[104:107]
	v_mfma_f32_16x16x32_bf16 v[96:99], v[210:213], v[174:177], v[96:99]
	v_mfma_f32_16x16x32_bf16 v[88:91], v[202:205], v[182:185], v[88:91]
	v_mfma_f32_16x16x32_bf16 v[80:83], v[210:213], v[182:185], v[80:83]
	v_mfma_f32_16x16x32_bf16 v[72:75], v[202:205], v[190:193], v[72:75]
	v_mfma_f32_16x16x32_bf16 v[64:67], v[210:213], v[190:193], v[64:67]
	v_mfma_f32_16x16x32_bf16 v[120:123], v[206:209], v[170:173], v[120:123]
	v_mfma_f32_16x16x32_bf16 v[112:115], v[214:217], v[170:173], v[112:115]
	v_mfma_f32_16x16x32_bf16 v[104:107], v[206:209], v[178:181], v[104:107]
	v_mfma_f32_16x16x32_bf16 v[96:99], v[214:217], v[178:181], v[96:99]
	v_mfma_f32_16x16x32_bf16 v[88:91], v[206:209], v[186:189], v[88:91]
	v_mfma_f32_16x16x32_bf16 v[80:83], v[214:217], v[186:189], v[80:83]
	v_mfma_f32_16x16x32_bf16 v[72:75], v[206:209], v[194:197], v[72:75]
	v_mfma_f32_16x16x32_bf16 v[64:67], v[214:217], v[194:197], v[64:67]
	s_barrier
	s_setprio 0
	s_mov_b32 m0, s13
	ds_read_b128 v[166:169], v148 offset:16384
	ds_read_b128 v[170:173], v148 offset:17408
	ds_read_b128 v[174:177], v148 offset:18432
	ds_read_b128 v[178:181], v148 offset:19456
	ds_read_b128 v[182:185], v148 offset:20480
	ds_read_b128 v[186:189], v148 offset:21504
	ds_read_b128 v[190:193], v148 offset:22528
	ds_read_b128 v[194:197], v148 offset:23552
	global_load_lds_dwordx4 v134, s[22:23]
	s_mov_b32 m0, s28
	s_nop 0
	global_load_lds_dwordx4 v130, s[22:23]
	s_setprio 1
	s_barrier
	s_waitcnt lgkmcnt(0)
	v_mfma_f32_16x16x32_bf16 v[60:63], v[150:153], v[166:169], v[60:63]
	v_mfma_f32_16x16x32_bf16 v[56:59], v[158:161], v[166:169], v[56:59]
	v_mfma_f32_16x16x32_bf16 v[44:47], v[150:153], v[174:177], v[44:47]
	v_mfma_f32_16x16x32_bf16 v[40:43], v[158:161], v[174:177], v[40:43]
	v_mfma_f32_16x16x32_bf16 v[28:31], v[150:153], v[182:185], v[28:31]
	v_mfma_f32_16x16x32_bf16 v[24:27], v[158:161], v[182:185], v[24:27]
	v_mfma_f32_16x16x32_bf16 v[12:15], v[150:153], v[190:193], v[12:15]
	v_mfma_f32_16x16x32_bf16 v[8:11], v[158:161], v[190:193], v[8:11]
	v_mfma_f32_16x16x32_bf16 v[60:63], v[154:157], v[170:173], v[60:63]
	v_mfma_f32_16x16x32_bf16 v[56:59], v[162:165], v[170:173], v[56:59]
	v_mfma_f32_16x16x32_bf16 v[44:47], v[154:157], v[178:181], v[44:47]
	v_mfma_f32_16x16x32_bf16 v[40:43], v[162:165], v[178:181], v[40:43]
	v_mfma_f32_16x16x32_bf16 v[28:31], v[154:157], v[186:189], v[28:31]
	v_mfma_f32_16x16x32_bf16 v[24:27], v[162:165], v[186:189], v[24:27]
	v_mfma_f32_16x16x32_bf16 v[12:15], v[154:157], v[194:197], v[12:15]
	v_mfma_f32_16x16x32_bf16 v[8:11], v[162:165], v[194:197], v[8:11]
	s_barrier
	s_setprio 0
	s_add_u32 s16, s18, 0x40000
	s_addc_u32 s17, s19, 0
	s_add_i32 s20, s41, s25
	s_mov_b32 m0, s20
	s_nop 0
	global_load_lds_dwordx4 v132, s[16:17]
	s_add_i32 m0, s20, 0x2000
	s_nop 0
	global_load_lds_dwordx4 v128, s[16:17]
	s_add_u32 s16, s22, 0x40000
	s_addc_u32 s17, s23, 0
	s_mov_b32 m0, s29
	s_nop 0
	global_load_lds_dwordx4 v134, s[16:17]
	s_mov_b32 m0, s33
	s_nop 0
	global_load_lds_dwordx4 v130, s[16:17]
	s_waitcnt vmcnt(10)
	s_setprio 1
	s_barrier
; #define PG8_STAGE(bufoff, gbase, voff) do { _Pragma("unroll") for (int _i = 0; _i < 2; ++_i) \
;         __builtin_amdgcn_global_load_lds((const unsigned*)((const char*)(gbase) + (voff)[_i]), (LAS unsigned*)(lds + (bufoff) + ldsw + _i * 8192), 16, 0, 0); } while (0)
; #define PG8_LDA(dst, b, h) do { _Pragma("unroll") for (int m = 0; m < 4; ++m) _Pragma("unroll") for (int k = 0; k < 2; ++k) dst[m][k] = *(const LAS bf16x8*)(lds + PG8_SA(b, h) + aoff + m * 2048 + k * 1024); } while (0)
; #define PG8_LDB(dst, b, h) do { _Pragma("unroll") for (int n = 0; n < 2; ++n) _Pragma("unroll") for (int k = 0; k < 2; ++k) dst[n][k] = *(const LAS bf16x8*)(lds + PG8_SB(b, h) + boff + n * 2048 + k * 1024); } while (0)
; #define PG8_MMA(ai, bj, At, Bt) do { __builtin_amdgcn_s_setprio(1); _Pragma("unroll") for (int m = 0; m < 4; ++m) _Pragma("unroll") for (int n = 0; n < 2; ++n) _Pragma("unroll") for (int k = 0; k < 2; ++k) \
;         acc[ai][bj][m][n] = __builtin_amdgcn_mfma_f32_16x16x32_bf16(Bt[n][k], At[m][k], acc[ai][bj][m][n], 0, 0, 0); __builtin_amdgcn_s_setprio(0); } while (0)
; #define PG8_WAIT_V(n) asm volatile("s_waitcnt vmcnt(" #n ")" ::: "memory")
; #define PG8_WAIT_L(n) asm volatile("s_waitcnt lgkmcnt(" #n ")" ::: "memory")
; #define PG8_BAR __builtin_amdgcn_s_barrier()
; #define PG8_SCHED __builtin_amdgcn_sched_barrier(0)
; template <class Epi, class Sched>
; __device__ __forceinline__ void gemm_phase(LAS unsigned char* lds, const Gemm g, const Sched& S, const Epi& E) {
;     ...
;             PG8_WAIT_V(6); PG8_BAR; PG8_MMA(1, 1, At, B1); PG8_BAR;
;             PG8_LDB(B0, 1, 0); PG8_SCHED; PG8_LDA(At, 1, 0); PG8_STAGE(PG8_SA(0, 1), a2 + hstep, voffA);
;             PG8_WAIT_L(8); PG8_BAR; PG8_WAIT_L(0); PG8_MMA(0, 0, At, B0); PG8_BAR; PG8_SCHED;
;             PG8_LDB(B1, 1, 1); PG8_STAGE(PG8_SB(1, 0), b3, voffB);
;             PG8_BAR; PG8_WAIT_L(0); PG8_MMA(0, 1, At, B1); PG8_BAR;
;             PG8_LDA(At, 1, 1); PG8_STAGE(PG8_SA(1, 0), a3, voffA);
;             PG8_BAR; PG8_WAIT_L(0); PG8_MMA(1, 0, At, B0); PG8_BAR; PG8_SCHED;
	v_mfma_f32_16x16x32_bf16 v[52:55], v[202:205], v[166:169], v[52:55]
	v_mfma_f32_16x16x32_bf16 v[48:51], v[210:213], v[166:169], v[48:51]
	v_mfma_f32_16x16x32_bf16 v[36:39], v[202:205], v[174:177], v[36:39]
	v_mfma_f32_16x16x32_bf16 v[32:35], v[210:213], v[174:177], v[32:35]
	v_mfma_f32_16x16x32_bf16 v[20:23], v[202:205], v[182:185], v[20:23]
	v_mfma_f32_16x16x32_bf16 v[16:19], v[210:213], v[182:185], v[16:19]
	v_mfma_f32_16x16x32_bf16 v[4:7], v[202:205], v[190:193], v[4:7]
	v_mfma_f32_16x16x32_bf16 v[0:3], v[210:213], v[190:193], v[0:3]
	v_mfma_f32_16x16x32_bf16 v[52:55], v[206:209], v[170:173], v[52:55]
	v_mfma_f32_16x16x32_bf16 v[48:51], v[214:217], v[170:173], v[48:51]
	v_mfma_f32_16x16x32_bf16 v[36:39], v[206:209], v[178:181], v[36:39]
	v_mfma_f32_16x16x32_bf16 v[32:35], v[214:217], v[178:181], v[32:35]
	v_mfma_f32_16x16x32_bf16 v[20:23], v[206:209], v[186:189], v[20:23]
	v_mfma_f32_16x16x32_bf16 v[16:19], v[214:217], v[186:189], v[16:19]
	v_mfma_f32_16x16x32_bf16 v[4:7], v[206:209], v[194:197], v[4:7]
	v_mfma_f32_16x16x32_bf16 v[0:3], v[214:217], v[194:197], v[0:3]
	s_barrier
	s_setprio 0
	s_add_i32 s20, 0, 0x18000
	ds_read_b128 v[150:153], v149 offset:16384
	ds_read_b128 v[154:157], v149 offset:17408
	ds_read_b128 v[158:161], v149 offset:18432
	ds_read_b128 v[162:165], v149 offset:19456
	ds_read_b128 v[166:169], v148 offset:32768
	ds_read_b128 v[170:173], v148 offset:33792
	ds_read_b128 v[174:177], v148 offset:34816
	ds_read_b128 v[178:181], v148 offset:35840
	ds_read_b128 v[182:185], v148 offset:36864
	ds_read_b128 v[186:189], v148 offset:37888
	ds_read_b128 v[190:193], v148 offset:38912
	ds_read_b128 v[194:197], v148 offset:39936
	s_waitcnt lgkmcnt(8)
	s_waitcnt vmcnt(8)
	s_setprio 1
	s_barrier
	s_waitcnt lgkmcnt(0)
	v_mfma_f32_16x16x32_bf16 v[124:127], v[150:153], v[166:169], v[124:127]
	v_mfma_f32_16x16x32_bf16 v[116:119], v[158:161], v[166:169], v[116:119]
	v_mfma_f32_16x16x32_bf16 v[108:111], v[150:153], v[174:177], v[108:111]
	v_mfma_f32_16x16x32_bf16 v[100:103], v[158:161], v[174:177], v[100:103]
	v_mfma_f32_16x16x32_bf16 v[92:95], v[150:153], v[182:185], v[92:95]
	v_mfma_f32_16x16x32_bf16 v[84:87], v[158:161], v[182:185], v[84:87]
	v_mfma_f32_16x16x32_bf16 v[76:79], v[150:153], v[190:193], v[76:79]
	v_mfma_f32_16x16x32_bf16 v[68:71], v[158:161], v[190:193], v[68:71]
	v_mfma_f32_16x16x32_bf16 v[124:127], v[154:157], v[170:173], v[124:127]
	v_mfma_f32_16x16x32_bf16 v[116:119], v[162:165], v[170:173], v[116:119]
	v_mfma_f32_16x16x32_bf16 v[108:111], v[154:157], v[178:181], v[108:111]
	v_mfma_f32_16x16x32_bf16 v[100:103], v[162:165], v[178:181], v[100:103]
	v_mfma_f32_16x16x32_bf16 v[92:95], v[154:157], v[186:189], v[92:95]
	v_mfma_f32_16x16x32_bf16 v[84:87], v[162:165], v[186:189], v[84:87]
	v_mfma_f32_16x16x32_bf16 v[76:79], v[154:157], v[194:197], v[76:79]
	v_mfma_f32_16x16x32_bf16 v[68:71], v[162:165], v[194:197], v[68:71]
	s_barrier
	s_setprio 0
	s_add_i32 s21, 0, 0x1c000
	s_add_i32 s16, s20, s25
	s_add_u32 s0, s18, 0x80
	s_addc_u32 s1, s19, 0
	s_mov_b32 m0, s16
	ds_read_b128 v[202:205], v149 offset:32768
	ds_read_b128 v[206:209], v149 offset:33792
	ds_read_b128 v[210:213], v149 offset:34816
	ds_read_b128 v[214:217], v149 offset:35840
	global_load_lds_dwordx4 v132, s[0:1]
	s_add_i32 m0, s16, 0x2000
	s_nop 0
	global_load_lds_dwordx4 v128, s[0:1]
	s_waitcnt vmcnt(8)
	s_setprio 1
	s_barrier
	s_waitcnt lgkmcnt(0)
	v_mfma_f32_16x16x32_bf16 v[120:123], v[202:205], v[166:169], v[120:123]
	v_mfma_f32_16x16x32_bf16 v[112:115], v[210:213], v[166:169], v[112:115]
	v_mfma_f32_16x16x32_bf16 v[104:107], v[202:205], v[174:177], v[104:107]
	v_mfma_f32_16x16x32_bf16 v[96:99], v[210:213], v[174:177], v[96:99]
	v_mfma_f32_16x16x32_bf16 v[88:91], v[202:205], v[182:185], v[88:91]
	v_mfma_f32_16x16x32_bf16 v[80:83], v[210:213], v[182:185], v[80:83]
	v_mfma_f32_16x16x32_bf16 v[72:75], v[202:205], v[190:193], v[72:75]
	v_mfma_f32_16x16x32_bf16 v[64:67], v[210:213], v[190:193], v[64:67]
	v_mfma_f32_16x16x32_bf16 v[120:123], v[206:209], v[170:173], v[120:123]
	v_mfma_f32_16x16x32_bf16 v[112:115], v[214:217], v[170:173], v[112:115]
	v_mfma_f32_16x16x32_bf16 v[104:107], v[206:209], v[178:181], v[104:107]
	v_mfma_f32_16x16x32_bf16 v[96:99], v[214:217], v[178:181], v[96:99]
	v_mfma_f32_16x16x32_bf16 v[88:91], v[206:209], v[186:189], v[88:91]
	v_mfma_f32_16x16x32_bf16 v[80:83], v[214:217], v[186:189], v[80:83]
	v_mfma_f32_16x16x32_bf16 v[72:75], v[206:209], v[194:197], v[72:75]
	v_mfma_f32_16x16x32_bf16 v[64:67], v[214:217], v[194:197], v[64:67]
	s_barrier
	s_setprio 0
	s_mov_b32 m0, s36
	s_add_u32 s0, s22, 0x80
	s_addc_u32 s1, s23, 0
	ds_read_b128 v[166:169], v148 offset:49152
	ds_read_b128 v[170:173], v148 offset:50176
	ds_read_b128 v[174:177], v148 offset:51200
	ds_read_b128 v[178:181], v148 offset:52224
	ds_read_b128 v[182:185], v148 offset:53248
	ds_read_b128 v[186:189], v148 offset:54272
	ds_read_b128 v[190:193], v148 offset:55296
	ds_read_b128 v[194:197], v148 offset:56320
	global_load_lds_dwordx4 v134, s[0:1]
	s_mov_b32 m0, s37
	s_nop 0
	global_load_lds_dwordx4 v130, s[0:1]
	s_setprio 1
	s_barrier
; __device__ __forceinline__ unsigned cvt_pk_bf16(float lo, float hi) { unsigned r; asm volatile("v_cvt_pk_bf16_f32 %0, %1, %2" : "=v"(r) : "v"(lo), "v"(hi)); return r; }
; __device__ __forceinline__ float silu_f(float a) { return a * __builtin_amdgcn_rcpf(1.0f + __expf(-a)); }
; #define PG8_STAGE(bufoff, gbase, voff) do { _Pragma("unroll") for (int _i = 0; _i < 2; ++_i) \
;         __builtin_amdgcn_global_load_lds((const unsigned*)((const char*)(gbase) + (voff)[_i]), (LAS unsigned*)(lds + (bufoff) + ldsw + _i * 8192), 16, 0, 0); } while (0)
; #define PG8_MMA(ai, bj, At, Bt) do { __builtin_amdgcn_s_setprio(1); _Pragma("unroll") for (int m = 0; m < 4; ++m) _Pragma("unroll") for (int n = 0; n < 2; ++n) _Pragma("unroll") for (int k = 0; k < 2; ++k) \
;         acc[ai][bj][m][n] = __builtin_amdgcn_mfma_f32_16x16x32_bf16(Bt[n][k], At[m][k], acc[ai][bj][m][n], 0, 0, 0); __builtin_amdgcn_s_setprio(0); } while (0)
; #define PG8_WAIT_V(n) asm volatile("s_waitcnt vmcnt(" #n ")" ::: "memory")
; #define PG8_WAIT_L(n) asm volatile("s_waitcnt lgkmcnt(" #n ")" ::: "memory")
; template <class Epi, class Sched>
; __device__ __forceinline__ void gemm_phase(LAS unsigned char* lds, const Gemm g, const Sched& S, const Epi& E) {
;     ...
;             PG8_BAR; PG8_WAIT_L(0); PG8_MMA(1, 0, At, B0); PG8_BAR; PG8_SCHED;
;             PG8_STAGE(PG8_SB(1, 1), b3 + hstep, voffB);
;             PG8_WAIT_V(6); PG8_BAR; PG8_MMA(1, 1, At, B1); PG8_BAR;
;         }
;         E(acc, cur, wr, wc, fr, fq);
;         if (!has_next) break;
;     __device__ __forceinline__ void operator()(const AccT& acc, const Unit& u, int wr, int wc, int fr, int fq) const {
;     ...
;         const int row0 = u.pm * 256 + wr * 64 + fr, hc0 = u.pn * 128 + wc * 32 + 8 * fq;
; #pragma unroll
;         for (int ai = 0; ai < 2; ++ai)
; #pragma unroll
;             for (int m = 0; m < 4; ++m) {
;                 const f32x4 a0 = acc[ai][0][m][0], a1 = acc[ai][0][m][1], b0 = acc[ai][1][m][0], b1 = acc[ai][1][m][1];
;                 u32x4 w;
;                 w.x = cvt_pk_bf16(silu_f(a0[0]) * b0[0], silu_f(a0[1]) * b0[1]); w.y = cvt_pk_bf16(silu_f(a0[2]) * b0[2], silu_f(a0[3]) * b0[3]);
;                 w.z = cvt_pk_bf16(silu_f(a1[0]) * b1[0], silu_f(a1[1]) * b1[1]); w.w = cvt_pk_bf16(silu_f(a1[2]) * b1[2], silu_f(a1[3]) * b1[3]);
;                 *(u32x4*)(H + (size_t)(row0 + ai * 128 + m * 16) * DFF + hc0) = w;
;             }
	s_waitcnt lgkmcnt(0)
	v_mfma_f32_16x16x32_bf16 v[60:63], v[150:153], v[166:169], v[60:63]
	v_mfma_f32_16x16x32_bf16 v[56:59], v[158:161], v[166:169], v[56:59]
	v_mfma_f32_16x16x32_bf16 v[44:47], v[150:153], v[174:177], v[44:47]
	v_mfma_f32_16x16x32_bf16 v[40:43], v[158:161], v[174:177], v[40:43]
	v_mfma_f32_16x16x32_bf16 v[28:31], v[150:153], v[182:185], v[28:31]
	v_mfma_f32_16x16x32_bf16 v[24:27], v[158:161], v[182:185], v[24:27]
	v_mfma_f32_16x16x32_bf16 v[12:15], v[150:153], v[190:193], v[12:15]
	v_mfma_f32_16x16x32_bf16 v[8:11], v[158:161], v[190:193], v[8:11]
	v_mfma_f32_16x16x32_bf16 v[60:63], v[154:157], v[170:173], v[60:63]
	v_mfma_f32_16x16x32_bf16 v[56:59], v[162:165], v[170:173], v[56:59]
	v_mfma_f32_16x16x32_bf16 v[44:47], v[154:157], v[178:181], v[44:47]
	v_mfma_f32_16x16x32_bf16 v[40:43], v[162:165], v[178:181], v[40:43]
	v_mfma_f32_16x16x32_bf16 v[28:31], v[154:157], v[186:189], v[28:31]
	v_mfma_f32_16x16x32_bf16 v[24:27], v[162:165], v[186:189], v[24:27]
	v_mfma_f32_16x16x32_bf16 v[12:15], v[154:157], v[194:197], v[12:15]
	v_mfma_f32_16x16x32_bf16 v[8:11], v[162:165], v[194:197], v[8:11]
	s_barrier
	s_setprio 0
	s_add_u32 s16, s18, 0x40080
	s_addc_u32 s17, s19, 0
	s_add_i32 s18, s21, s25
	s_mov_b32 m0, s18
	s_nop 0
	global_load_lds_dwordx4 v132, s[16:17]
	s_add_i32 m0, s18, 0x2000
	s_nop 0
	global_load_lds_dwordx4 v128, s[16:17]
	s_waitcnt vmcnt(8)
	s_setprio 1
	s_barrier
	v_mfma_f32_16x16x32_bf16 v[52:55], v[202:205], v[166:169], v[52:55]
	v_mfma_f32_16x16x32_bf16 v[48:51], v[210:213], v[166:169], v[48:51]
	v_mfma_f32_16x16x32_bf16 v[36:39], v[202:205], v[174:177], v[36:39]
	v_mfma_f32_16x16x32_bf16 v[32:35], v[210:213], v[174:177], v[32:35]
	v_mfma_f32_16x16x32_bf16 v[20:23], v[202:205], v[182:185], v[20:23]
	v_mfma_f32_16x16x32_bf16 v[16:19], v[210:213], v[182:185], v[16:19]
	v_mfma_f32_16x16x32_bf16 v[4:7], v[202:205], v[190:193], v[4:7]
	v_mfma_f32_16x16x32_bf16 v[0:3], v[210:213], v[190:193], v[0:3]
	v_mfma_f32_16x16x32_bf16 v[52:55], v[206:209], v[170:173], v[52:55]
	v_mfma_f32_16x16x32_bf16 v[48:51], v[214:217], v[170:173], v[48:51]
	v_mfma_f32_16x16x32_bf16 v[36:39], v[206:209], v[178:181], v[36:39]
	v_mfma_f32_16x16x32_bf16 v[32:35], v[214:217], v[178:181], v[32:35]
	v_mfma_f32_16x16x32_bf16 v[20:23], v[206:209], v[186:189], v[20:23]
	v_mfma_f32_16x16x32_bf16 v[16:19], v[214:217], v[186:189], v[16:19]
	v_mfma_f32_16x16x32_bf16 v[4:7], v[206:209], v[194:197], v[4:7]
	v_mfma_f32_16x16x32_bf16 v[0:3], v[214:217], v[194:197], v[0:3]
	s_add_i32 s48, s48, 2
	s_cmp_gt_u32 s48, 13
	s_cbranch_scc1 .Lconc_last_g0
	s_barrier
	s_setprio 0
	s_add_u32 s14, s14, 0x100
	s_addc_u32 s15, s15, 0
	s_add_u32 s46, s46, 0x100
	s_addc_u32 s47, s47, 0
	s_branch .LBB0_235
.Lconc_last_g0:
	v_readfirstlane_b32 s5, v200
	s_nop 3
	s_cmp_gt_u32 s5, 0xff
	s_cbranch_scc1 .Lconc_epi1_g0
	s_barrier
	s_setprio 0
	v_mul_f32_e32 v152, 0xbfb8aa3b, v124
	v_mov_b32_e32 v151, v145
	v_mov_b32_e32 v150, v144
	s_lshl_b32 s5, s12, 8
	v_exp_f32_e32 v153, v152
	v_mul_f32_e32 v152, 0xbfb8aa3b, v125
	s_add_i32 s5, s5, s34
	v_exp_f32_e32 v154, v152
	v_add_u32_e32 v150, s5, v150
	s_lshl_b32 s5, s43, 7
	s_or_b32 s5, s5, s35
	v_lshl_add_u32 v152, v151, 3, s5
	v_add_f32_e32 v151, 1.0, v153
	v_rcp_f32_e32 v151, v151
	v_add_f32_e32 v153, 1.0, v154
	v_rcp_f32_e32 v154, v153
	v_ashrrev_i32_e32 v153, 31, v152
	v_mul_f32_e32 v124, v124, v151
	v_mul_f32_e32 v120, v124, v120
	v_mul_f32_e32 v124, v125, v154
	v_mul_f32_e32 v125, 0xbfb8aa3b, v126
	v_exp_f32_e32 v125, v125
	v_mul_f32_e32 v151, 0xbfb8aa3b, v127
	v_exp_f32_e32 v151, v151
	v_mul_f32_e32 v121, v124, v121
	v_add_f32_e32 v124, 1.0, v125
	v_rcp_f32_e32 v124, v124
	v_add_f32_e32 v125, 1.0, v151
	v_rcp_f32_e32 v125, v125
	v_cvt_pk_bf16_f32 v120, v120, v121
	v_mul_f32_e32 v121, v126, v124
	v_mul_f32_e32 v124, 0xbfb8aa3b, v116
	v_mul_f32_e32 v121, v121, v122
	v_mul_f32_e32 v122, v127, v125
	v_exp_f32_e32 v124, v124
	v_mul_f32_e32 v125, 0xbfb8aa3b, v117
	v_exp_f32_e32 v125, v125
	v_mul_f32_e32 v122, v122, v123
	v_add_f32_e32 v123, 1.0, v124
	v_rcp_f32_e32 v123, v123
	v_add_f32_e32 v124, 1.0, v125
	v_rcp_f32_e32 v124, v124
	v_cvt_pk_bf16_f32 v121, v121, v122
	v_mul_f32_e32 v116, v116, v123
	v_mul_f32_e32 v112, v116, v112
	v_mul_f32_e32 v116, v117, v124
	v_mul_f32_e32 v117, 0xbfb8aa3b, v118
	v_exp_f32_e32 v117, v117
	v_mul_f32_e32 v122, 0xbfb8aa3b, v119
	v_exp_f32_e32 v122, v122
	v_mul_f32_e32 v113, v116, v113
	v_add_f32_e32 v116, 1.0, v117
	v_rcp_f32_e32 v116, v116
	v_add_f32_e32 v117, 1.0, v122
	v_rcp_f32_e32 v117, v117
	v_cvt_pk_bf16_f32 v122, v112, v113
	v_mul_f32_e32 v112, v118, v116
	v_mul_f32_e32 v118, 0xbfb8aa3b, v108
	v_mul_f32_e32 v113, v119, v117
	v_exp_f32_e32 v118, v118
	v_mul_f32_e32 v119, 0xbfb8aa3b, v109
	v_exp_f32_e32 v119, v119
	v_mul_f32_e32 v112, v112, v114
	v_add_f32_e32 v118, 1.0, v118
	v_rcp_f32_e32 v118, v118
	v_add_f32_e32 v119, 1.0, v119
	v_rcp_f32_e32 v119, v119
	v_mul_f32_e32 v113, v113, v115
	v_cvt_pk_bf16_f32 v123, v112, v113
	v_mov_b64_e32 v[112:113], s[82:83]
	v_mad_i64_i32 v[116:117], s[14:15], v150, s42, v[112:113]
	v_lshlrev_b64 v[114:115], 1, v[152:153]
	v_mul_f32_e32 v108, v108, v118
	v_lshl_add_u64 v[116:117], v[116:117], 0, v[114:115]
	v_mul_f32_e32 v104, v108, v104
	v_mul_f32_e32 v108, v109, v119
	v_mul_f32_e32 v109, 0xbfb8aa3b, v110
	global_store_dwordx4 v[116:117], v[120:123], off
	v_exp_f32_e32 v109, v109
	v_mul_f32_e32 v116, 0xbfb8aa3b, v111
	v_exp_f32_e32 v116, v116
	v_mul_f32_e32 v105, v108, v105
	v_add_f32_e32 v108, 1.0, v109
	v_rcp_f32_e32 v108, v108
	v_add_f32_e32 v109, 1.0, v116
	v_rcp_f32_e32 v109, v109
	v_cvt_pk_bf16_f32 v104, v104, v105
	v_mul_f32_e32 v105, v110, v108
; __device__ __forceinline__ unsigned cvt_pk_bf16(float lo, float hi) { unsigned r; asm volatile("v_cvt_pk_bf16_f32 %0, %1, %2" : "=v"(r) : "v"(lo), "v"(hi)); return r; }
; __device__ __forceinline__ float silu_f(float a) { return a * __builtin_amdgcn_rcpf(1.0f + __expf(-a)); }
;     __device__ __forceinline__ void operator()(const AccT& acc, const Unit& u, int wr, int wc, int fr, int fq) const {
;     ...
;         for (int ai = 0; ai < 2; ++ai)
; #pragma unroll
;             for (int m = 0; m < 4; ++m) {
;                 const f32x4 a0 = acc[ai][0][m][0], a1 = acc[ai][0][m][1], b0 = acc[ai][1][m][0], b1 = acc[ai][1][m][1];
;                 u32x4 w;
;                 w.x = cvt_pk_bf16(silu_f(a0[0]) * b0[0], silu_f(a0[1]) * b0[1]); w.y = cvt_pk_bf16(silu_f(a0[2]) * b0[2], silu_f(a0[3]) * b0[3]);
;                 w.z = cvt_pk_bf16(silu_f(a1[0]) * b1[0], silu_f(a1[1]) * b1[1]); w.w = cvt_pk_bf16(silu_f(a1[2]) * b1[2], silu_f(a1[3]) * b1[3]);
;                 *(u32x4*)(H + (size_t)(row0 + ai * 128 + m * 16) * DFF + hc0) = w;
;             }
	v_mul_f32_e32 v108, 0xbfb8aa3b, v100
	v_mul_f32_e32 v105, v105, v106
	v_mul_f32_e32 v106, v111, v109
	v_exp_f32_e32 v108, v108
	v_mul_f32_e32 v109, 0xbfb8aa3b, v101
	v_exp_f32_e32 v109, v109
	v_mul_f32_e32 v106, v106, v107
	v_add_f32_e32 v107, 1.0, v108
	v_rcp_f32_e32 v107, v107
	v_add_f32_e32 v108, 1.0, v109
	v_rcp_f32_e32 v108, v108
	v_cvt_pk_bf16_f32 v105, v105, v106
	v_mul_f32_e32 v100, v100, v107
	v_mul_f32_e32 v96, v100, v96
	v_mul_f32_e32 v100, v101, v108
	v_mul_f32_e32 v101, 0xbfb8aa3b, v102
	v_exp_f32_e32 v101, v101
	v_mul_f32_e32 v106, 0xbfb8aa3b, v103
	v_exp_f32_e32 v106, v106
	v_mul_f32_e32 v97, v100, v97
	v_add_f32_e32 v100, 1.0, v101
	v_rcp_f32_e32 v100, v100
	v_add_f32_e32 v101, 1.0, v106
	v_rcp_f32_e32 v101, v101
	v_cvt_pk_bf16_f32 v106, v96, v97
	v_mul_f32_e32 v96, v102, v100
	v_mul_f32_e32 v96, v96, v98
	v_mul_f32_e32 v97, v103, v101
	v_mul_f32_e32 v98, 0xbfb8aa3b, v92
	v_mul_f32_e32 v97, v97, v99
	v_exp_f32_e32 v98, v98
	v_mul_f32_e32 v99, 0xbfb8aa3b, v93
	v_exp_f32_e32 v99, v99
	v_cvt_pk_bf16_f32 v107, v96, v97
	v_add_f32_e32 v98, 1.0, v98
	v_rcp_f32_e32 v98, v98
	v_add_f32_e32 v99, 1.0, v99
	v_rcp_f32_e32 v99, v99
	v_add_u32_e32 v96, 16, v150
	v_mad_i64_i32 v[96:97], s[14:15], v96, s42, v[112:113]
	v_mul_f32_e32 v92, v92, v98
	v_lshl_add_u64 v[96:97], v[96:97], 0, v[114:115]
	v_mul_f32_e32 v88, v92, v88
	v_mul_f32_e32 v92, v93, v99
	v_mul_f32_e32 v93, 0xbfb8aa3b, v94
	global_store_dwordx4 v[96:97], v[104:107], off
	v_exp_f32_e32 v93, v93
	v_mul_f32_e32 v96, 0xbfb8aa3b, v95
	v_exp_f32_e32 v96, v96
	v_mul_f32_e32 v89, v92, v89
	v_add_f32_e32 v92, 1.0, v93
	v_rcp_f32_e32 v92, v92
	v_add_f32_e32 v93, 1.0, v96
	v_rcp_f32_e32 v93, v93
	v_cvt_pk_bf16_f32 v88, v88, v89
	v_mul_f32_e32 v89, v94, v92
	v_mul_f32_e32 v92, 0xbfb8aa3b, v84
	v_mul_f32_e32 v89, v89, v90
	v_mul_f32_e32 v90, v95, v93
	v_exp_f32_e32 v92, v92
	v_mul_f32_e32 v93, 0xbfb8aa3b, v85
	v_exp_f32_e32 v93, v93
	v_mul_f32_e32 v90, v90, v91
	v_add_f32_e32 v91, 1.0, v92
	v_rcp_f32_e32 v91, v91
	v_add_f32_e32 v92, 1.0, v93
	v_rcp_f32_e32 v92, v92
	v_cvt_pk_bf16_f32 v89, v89, v90
	v_mul_f32_e32 v84, v84, v91
	v_mul_f32_e32 v80, v84, v80
	v_mul_f32_e32 v84, v85, v92
	v_mul_f32_e32 v85, 0xbfb8aa3b, v86
	v_exp_f32_e32 v85, v85
	v_mul_f32_e32 v90, 0xbfb8aa3b, v87
	v_exp_f32_e32 v90, v90
	v_mul_f32_e32 v81, v84, v81
	v_add_f32_e32 v84, 1.0, v85
	v_rcp_f32_e32 v84, v84
	v_add_f32_e32 v85, 1.0, v90
	v_rcp_f32_e32 v85, v85
	v_cvt_pk_bf16_f32 v90, v80, v81
	v_mul_f32_e32 v80, v86, v84
	v_mul_f32_e32 v80, v80, v82
	v_mul_f32_e32 v81, v87, v85
	v_mul_f32_e32 v82, 0xbfb8aa3b, v76
	v_mul_f32_e32 v81, v81, v83
	v_exp_f32_e32 v82, v82
	v_mul_f32_e32 v83, 0xbfb8aa3b, v77
	v_exp_f32_e32 v83, v83
	v_cvt_pk_bf16_f32 v91, v80, v81
	v_add_f32_e32 v82, 1.0, v82
	v_rcp_f32_e32 v82, v82
	v_add_f32_e32 v83, 1.0, v83
	v_rcp_f32_e32 v83, v83
	v_add_u32_e32 v80, 32, v150
	v_mad_i64_i32 v[80:81], s[14:15], v80, s42, v[112:113]
	v_mul_f32_e32 v76, v76, v82
	v_lshl_add_u64 v[80:81], v[80:81], 0, v[114:115]
	v_mul_f32_e32 v72, v76, v72
	v_mul_f32_e32 v76, v77, v83
	v_mul_f32_e32 v77, 0xbfb8aa3b, v78
	global_store_dwordx4 v[80:81], v[88:91], off
	v_exp_f32_e32 v77, v77
	v_mul_f32_e32 v80, 0xbfb8aa3b, v79
	v_exp_f32_e32 v80, v80
	v_mul_f32_e32 v73, v76, v73
	v_add_f32_e32 v76, 1.0, v77
	v_rcp_f32_e32 v76, v76
	v_add_f32_e32 v77, 1.0, v80
	v_rcp_f32_e32 v77, v77
	v_cvt_pk_bf16_f32 v72, v72, v73
	v_mul_f32_e32 v73, v78, v76
	v_mul_f32_e32 v76, 0xbfb8aa3b, v68
	v_mul_f32_e32 v73, v73, v74
	v_mul_f32_e32 v74, v79, v77
	v_exp_f32_e32 v76, v76
	v_mul_f32_e32 v77, 0xbfb8aa3b, v69
	v_exp_f32_e32 v77, v77
	v_mul_f32_e32 v74, v74, v75
	v_add_f32_e32 v75, 1.0, v76
	v_rcp_f32_e32 v75, v75
	v_add_f32_e32 v76, 1.0, v77
	v_rcp_f32_e32 v76, v76
	v_cvt_pk_bf16_f32 v73, v73, v74
	v_mul_f32_e32 v68, v68, v75
	v_mul_f32_e32 v64, v68, v64
	v_mul_f32_e32 v68, v69, v76
	v_mul_f32_e32 v69, 0xbfb8aa3b, v70
	v_exp_f32_e32 v69, v69
	v_mul_f32_e32 v74, 0xbfb8aa3b, v71
	v_exp_f32_e32 v74, v74
	v_mul_f32_e32 v65, v68, v65
	v_add_f32_e32 v68, 1.0, v69
	v_rcp_f32_e32 v68, v68
	v_add_f32_e32 v69, 1.0, v74
	v_rcp_f32_e32 v69, v69
	v_cvt_pk_bf16_f32 v74, v64, v65
	v_mul_f32_e32 v64, v70, v68
	v_mul_f32_e32 v64, v64, v66
	v_mul_f32_e32 v65, v71, v69
	v_mul_f32_e32 v66, 0xbfb8aa3b, v60
	v_mul_f32_e32 v65, v65, v67
	v_exp_f32_e32 v66, v66
	v_mul_f32_e32 v67, 0xbfb8aa3b, v61
	v_cvt_pk_bf16_f32 v75, v64, v65
	v_add_u32_e32 v64, 48, v150
	v_exp_f32_e32 v67, v67
	v_mad_i64_i32 v[64:65], s[14:15], v64, s42, v[112:113]
	v_lshl_add_u64 v[64:65], v[64:65], 0, v[114:115]
	global_store_dwordx4 v[64:65], v[72:75], off
	v_add_f32_e32 v64, 1.0, v66
	v_rcp_f32_e32 v64, v64
	v_add_f32_e32 v65, 1.0, v67
	v_rcp_f32_e32 v65, v65
	v_add_u32_e32 v66, 0x80, v150
	v_mul_f32_e32 v60, v60, v64
	v_mul_f32_e32 v52, v60, v52
	v_mul_f32_e32 v60, v61, v65
	v_mul_f32_e32 v61, 0xbfb8aa3b, v62
	v_exp_f32_e32 v61, v61
	v_mul_f32_e32 v64, 0xbfb8aa3b, v63
	v_exp_f32_e32 v64, v64
	v_mul_f32_e32 v53, v60, v53
	v_add_f32_e32 v60, 1.0, v61
	v_rcp_f32_e32 v60, v60
	v_add_f32_e32 v61, 1.0, v64
	v_rcp_f32_e32 v61, v61
	v_cvt_pk_bf16_f32 v52, v52, v53
	v_mul_f32_e32 v53, v62, v60
	v_mul_f32_e32 v60, 0xbfb8aa3b, v56
	v_exp_f32_e32 v60, v60
	v_mul_f32_e32 v53, v53, v54
	v_mul_f32_e32 v54, v63, v61
	v_mul_f32_e32 v61, 0xbfb8aa3b, v57
	v_exp_f32_e32 v61, v61
	v_mul_f32_e32 v54, v54, v55
	v_add_f32_e32 v55, 1.0, v60
	v_rcp_f32_e32 v55, v55
	v_add_f32_e32 v60, 1.0, v61
	v_rcp_f32_e32 v60, v60
	v_cvt_pk_bf16_f32 v53, v53, v54
	v_mul_f32_e32 v54, v56, v55
	v_mul_f32_e32 v55, 0xbfb8aa3b, v58
	v_exp_f32_e32 v55, v55
	v_mul_f32_e32 v56, 0xbfb8aa3b, v59
	v_exp_f32_e32 v56, v56
; __device__ __forceinline__ unsigned cvt_pk_bf16(float lo, float hi) { unsigned r; asm volatile("v_cvt_pk_bf16_f32 %0, %1, %2" : "=v"(r) : "v"(lo), "v"(hi)); return r; }
; __device__ __forceinline__ float silu_f(float a) { return a * __builtin_amdgcn_rcpf(1.0f + __expf(-a)); }
; template <class Epi, class Sched>
; __device__ __forceinline__ void gemm_phase(LAS unsigned char* lds, const Gemm g, const Sched& S, const Epi& E) {
;     ...
;         E(acc, cur, wr, wc, fr, fq);
;         if (!has_next) break;
; #pragma unroll
;         for (int a = 0; a < 2; ++a)
; #pragma unroll
;             for (int b = 0; b < 2; ++b)
; #pragma unroll
;                 for (int m = 0; m < 4; ++m)
; #pragma unroll
;                     for (int n = 0; n < 2; ++n) acc[a][b][m][n] = (f32x4){0.f, 0.f, 0.f, 0.f};
;         cur = nxt; cA = nA; cB = nB; ++ui;
;     __device__ __forceinline__ void operator()(const AccT& acc, const Unit& u, int wr, int wc, int fr, int fq) const {
;     ...
;         for (int ai = 0; ai < 2; ++ai)
; #pragma unroll
;             for (int m = 0; m < 4; ++m) {
;                 const f32x4 a0 = acc[ai][0][m][0], a1 = acc[ai][0][m][1], b0 = acc[ai][1][m][0], b1 = acc[ai][1][m][1];
;                 u32x4 w;
;                 w.x = cvt_pk_bf16(silu_f(a0[0]) * b0[0], silu_f(a0[1]) * b0[1]); w.y = cvt_pk_bf16(silu_f(a0[2]) * b0[2], silu_f(a0[3]) * b0[3]);
;                 w.z = cvt_pk_bf16(silu_f(a1[0]) * b1[0], silu_f(a1[1]) * b1[1]); w.w = cvt_pk_bf16(silu_f(a1[2]) * b1[2], silu_f(a1[3]) * b1[3]);
;                 *(u32x4*)(H + (size_t)(row0 + ai * 128 + m * 16) * DFF + hc0) = w;
;             }
	v_mul_f32_e32 v48, v54, v48
	v_mul_f32_e32 v54, v57, v60
	v_mul_f32_e32 v49, v54, v49
	v_add_f32_e32 v54, 1.0, v55
	v_rcp_f32_e32 v55, v54
	v_add_f32_e32 v54, 1.0, v56
	v_rcp_f32_e32 v56, v54
	v_cvt_pk_bf16_f32 v54, v48, v49
	v_mul_f32_e32 v48, v58, v55
	v_mul_f32_e32 v48, v48, v50
	v_mul_f32_e32 v49, v59, v56
	v_mul_f32_e32 v50, 0xbfb8aa3b, v44
	v_mul_f32_e32 v49, v49, v51
	v_exp_f32_e32 v50, v50
	v_mul_f32_e32 v51, 0xbfb8aa3b, v45
	v_exp_f32_e32 v51, v51
	v_cvt_pk_bf16_f32 v55, v48, v49
	v_add_f32_e32 v50, 1.0, v50
	v_rcp_f32_e32 v50, v50
	v_add_f32_e32 v51, 1.0, v51
	v_rcp_f32_e32 v51, v51
	v_mad_i64_i32 v[48:49], s[14:15], v66, s42, v[112:113]
	v_mul_f32_e32 v44, v44, v50
	v_mul_f32_e32 v36, v44, v36
	v_mul_f32_e32 v44, v45, v51
	v_mul_f32_e32 v45, 0xbfb8aa3b, v46
	v_exp_f32_e32 v45, v45
	v_lshl_add_u64 v[48:49], v[48:49], 0, v[114:115]
	global_store_dwordx4 v[48:49], v[52:55], off
	v_mul_f32_e32 v48, 0xbfb8aa3b, v47
	v_exp_f32_e32 v48, v48
	v_mul_f32_e32 v37, v44, v37
	v_add_f32_e32 v44, 1.0, v45
	v_rcp_f32_e32 v44, v44
	v_add_f32_e32 v45, 1.0, v48
	v_rcp_f32_e32 v45, v45
	v_cvt_pk_bf16_f32 v36, v36, v37
	v_mul_f32_e32 v37, v46, v44
	v_mul_f32_e32 v44, 0xbfb8aa3b, v40
	v_exp_f32_e32 v44, v44
	v_mul_f32_e32 v37, v37, v38
	v_mul_f32_e32 v38, v47, v45
	v_mul_f32_e32 v45, 0xbfb8aa3b, v41
	v_exp_f32_e32 v45, v45
	v_mul_f32_e32 v38, v38, v39
	v_add_f32_e32 v39, 1.0, v44
	v_rcp_f32_e32 v39, v39
	v_add_f32_e32 v44, 1.0, v45
	v_rcp_f32_e32 v44, v44
	v_cvt_pk_bf16_f32 v37, v37, v38
	v_mul_f32_e32 v38, v40, v39
	v_mul_f32_e32 v39, 0xbfb8aa3b, v42
	v_exp_f32_e32 v39, v39
	v_mul_f32_e32 v40, 0xbfb8aa3b, v43
	v_exp_f32_e32 v40, v40
	v_mul_f32_e32 v32, v38, v32
	v_mul_f32_e32 v38, v41, v44
	v_mul_f32_e32 v33, v38, v33
	v_add_f32_e32 v38, 1.0, v39
	v_rcp_f32_e32 v39, v38
	v_add_f32_e32 v38, 1.0, v40
	v_rcp_f32_e32 v40, v38
	v_cvt_pk_bf16_f32 v38, v32, v33
	v_mul_f32_e32 v32, v42, v39
	v_mul_f32_e32 v32, v32, v34
	v_mul_f32_e32 v33, v43, v40
	v_mul_f32_e32 v34, 0xbfb8aa3b, v28
	v_mul_f32_e32 v33, v33, v35
	v_exp_f32_e32 v34, v34
	v_mul_f32_e32 v35, 0xbfb8aa3b, v29
	v_exp_f32_e32 v35, v35
	v_cvt_pk_bf16_f32 v39, v32, v33
	v_add_f32_e32 v34, 1.0, v34
	v_rcp_f32_e32 v34, v34
	v_add_f32_e32 v35, 1.0, v35
	v_rcp_f32_e32 v35, v35
	v_add_u32_e32 v32, 0x90, v150
	v_mul_f32_e32 v28, v28, v34
	v_mul_f32_e32 v20, v28, v20
	v_mul_f32_e32 v28, v29, v35
	v_mul_f32_e32 v29, 0xbfb8aa3b, v30
	v_exp_f32_e32 v29, v29
	v_mad_i64_i32 v[32:33], s[14:15], v32, s42, v[112:113]
	v_lshl_add_u64 v[32:33], v[32:33], 0, v[114:115]
	global_store_dwordx4 v[32:33], v[36:39], off
	v_mul_f32_e32 v32, 0xbfb8aa3b, v31
	v_exp_f32_e32 v32, v32
	v_mul_f32_e32 v21, v28, v21
	v_add_f32_e32 v28, 1.0, v29
	v_rcp_f32_e32 v28, v28
	v_add_f32_e32 v29, 1.0, v32
	v_rcp_f32_e32 v29, v29
	v_cvt_pk_bf16_f32 v20, v20, v21
	v_mul_f32_e32 v21, v30, v28
	v_mul_f32_e32 v28, 0xbfb8aa3b, v24
	v_exp_f32_e32 v28, v28
	v_mul_f32_e32 v21, v21, v22
	v_mul_f32_e32 v22, v31, v29
	v_mul_f32_e32 v29, 0xbfb8aa3b, v25
	v_exp_f32_e32 v29, v29
	v_mul_f32_e32 v22, v22, v23
	v_add_f32_e32 v23, 1.0, v28
	v_rcp_f32_e32 v23, v23
	v_add_f32_e32 v28, 1.0, v29
	v_rcp_f32_e32 v28, v28
	v_cvt_pk_bf16_f32 v21, v21, v22
	v_mul_f32_e32 v22, v24, v23
	v_mul_f32_e32 v23, 0xbfb8aa3b, v26
	v_exp_f32_e32 v23, v23
	v_mul_f32_e32 v24, 0xbfb8aa3b, v27
	v_exp_f32_e32 v24, v24
	v_mul_f32_e32 v16, v22, v16
	v_mul_f32_e32 v22, v25, v28
	v_mul_f32_e32 v17, v22, v17
	v_add_f32_e32 v22, 1.0, v23
	v_rcp_f32_e32 v23, v22
	v_add_f32_e32 v22, 1.0, v24
	v_rcp_f32_e32 v24, v22
	v_cvt_pk_bf16_f32 v22, v16, v17
	v_mul_f32_e32 v16, v26, v23
	v_mul_f32_e32 v16, v16, v18
	v_mul_f32_e32 v17, v27, v24
	v_mul_f32_e32 v18, 0xbfb8aa3b, v12
	v_mul_f32_e32 v17, v17, v19
	v_exp_f32_e32 v18, v18
	v_mul_f32_e32 v19, 0xbfb8aa3b, v13
	v_exp_f32_e32 v19, v19
	v_cvt_pk_bf16_f32 v23, v16, v17
	v_add_f32_e32 v18, 1.0, v18
	v_rcp_f32_e32 v18, v18
	v_add_f32_e32 v19, 1.0, v19
	v_rcp_f32_e32 v19, v19
	v_add_u32_e32 v16, 0xa0, v150
	v_mul_f32_e32 v12, v12, v18
	v_mul_f32_e32 v4, v12, v4
	v_mul_f32_e32 v12, v13, v19
	v_mul_f32_e32 v13, 0xbfb8aa3b, v14
	v_exp_f32_e32 v13, v13
	v_mad_i64_i32 v[16:17], s[14:15], v16, s42, v[112:113]
	v_lshl_add_u64 v[16:17], v[16:17], 0, v[114:115]
	global_store_dwordx4 v[16:17], v[20:23], off
	v_mul_f32_e32 v16, 0xbfb8aa3b, v15
	v_exp_f32_e32 v16, v16
	v_mul_f32_e32 v5, v12, v5
	v_add_f32_e32 v12, 1.0, v13
	v_rcp_f32_e32 v12, v12
	v_add_f32_e32 v13, 1.0, v16
	v_rcp_f32_e32 v13, v13
	v_cvt_pk_bf16_f32 v4, v4, v5
	v_mul_f32_e32 v5, v14, v12
	v_mul_f32_e32 v12, 0xbfb8aa3b, v8
	v_exp_f32_e32 v12, v12
	v_mul_f32_e32 v5, v5, v6
	v_mul_f32_e32 v6, v15, v13
	v_mul_f32_e32 v13, 0xbfb8aa3b, v9
	v_exp_f32_e32 v13, v13
	v_mul_f32_e32 v6, v6, v7
	v_add_f32_e32 v7, 1.0, v12
	v_rcp_f32_e32 v7, v7
	v_add_f32_e32 v12, 1.0, v13
	v_rcp_f32_e32 v12, v12
	v_cvt_pk_bf16_f32 v5, v5, v6
	v_mul_f32_e32 v6, v8, v7
	v_mul_f32_e32 v7, 0xbfb8aa3b, v10
	v_exp_f32_e32 v7, v7
	v_mul_f32_e32 v8, 0xbfb8aa3b, v11
	v_exp_f32_e32 v8, v8
	v_mul_f32_e32 v0, v6, v0
	v_mul_f32_e32 v6, v9, v12
	v_mul_f32_e32 v1, v6, v1
	v_add_f32_e32 v6, 1.0, v7
	v_rcp_f32_e32 v7, v6
	v_add_f32_e32 v6, 1.0, v8
	v_rcp_f32_e32 v8, v6
	v_cvt_pk_bf16_f32 v6, v0, v1
	v_mul_f32_e32 v0, v10, v7
	v_mul_f32_e32 v0, v0, v2
	v_mul_f32_e32 v1, v11, v8
	v_mul_f32_e32 v1, v1, v3
	v_cvt_pk_bf16_f32 v7, v0, v1
	v_add_u32_e32 v0, 0xb0, v150
	v_mad_i64_i32 v[0:1], s[14:15], v0, s42, v[112:113]
	v_lshl_add_u64 v[0:1], v[0:1], 0, v[114:115]
	s_and_b64 vcc, exec, s[2:3]
	s_mov_b32 s43, s4
	s_mov_b32 s12, s6
	s_mov_b64 s[18:19], s[10:11]
	s_mov_b64 s[14:15], s[8:9]
	global_store_dwordx4 v[0:1], v[4:7], off
	s_cbranch_vccz .LBB0_232
	s_branch .Lconc_end_g0
; __device__ __forceinline__ unsigned cvt_pk_bf16(float lo, float hi) { unsigned r; asm volatile("v_cvt_pk_bf16_f32 %0, %1, %2" : "=v"(r) : "v"(lo), "v"(hi)); return r; }
; __device__ __forceinline__ float silu_f(float a) { return a * __builtin_amdgcn_rcpf(1.0f + __expf(-a)); }
;     __device__ __forceinline__ void operator()(const AccT& acc, const Unit& u, int wr, int wc, int fr, int fq) const {
;     ...
;         const int row0 = u.pm * 256 + wr * 64 + fr, hc0 = u.pn * 128 + wc * 32 + 8 * fq;
; #pragma unroll
;         for (int ai = 0; ai < 2; ++ai)
; #pragma unroll
;             for (int m = 0; m < 4; ++m) {
;                 const f32x4 a0 = acc[ai][0][m][0], a1 = acc[ai][0][m][1], b0 = acc[ai][1][m][0], b1 = acc[ai][1][m][1];
;                 u32x4 w;
;                 w.x = cvt_pk_bf16(silu_f(a0[0]) * b0[0], silu_f(a0[1]) * b0[1]); w.y = cvt_pk_bf16(silu_f(a0[2]) * b0[2], silu_f(a0[3]) * b0[3]);
;                 w.z = cvt_pk_bf16(silu_f(a1[0]) * b1[0], silu_f(a1[1]) * b1[1]); w.w = cvt_pk_bf16(silu_f(a1[2]) * b1[2], silu_f(a1[3]) * b1[3]);
;                 *(u32x4*)(H + (size_t)(row0 + ai * 128 + m * 16) * DFF + hc0) = w;
;             }
.Lconc_epi1_g0:
	s_setprio 0
	v_mul_f32_e32 v152, 0xbfb8aa3b, v124
	v_mov_b32_e32 v151, v145
	v_mov_b32_e32 v150, v144
	s_lshl_b32 s5, s12, 8
	v_exp_f32_e32 v153, v152
	v_mul_f32_e32 v152, 0xbfb8aa3b, v125
	s_add_i32 s5, s5, s34
	v_exp_f32_e32 v154, v152
	v_add_u32_e32 v150, s5, v150
	s_lshl_b32 s5, s43, 7
	s_or_b32 s5, s5, s35
	v_lshl_add_u32 v152, v151, 3, s5
	v_add_f32_e32 v151, 1.0, v153
	v_rcp_f32_e32 v151, v151
	v_add_f32_e32 v153, 1.0, v154
	v_rcp_f32_e32 v154, v153
	v_ashrrev_i32_e32 v153, 31, v152
	v_mul_f32_e32 v124, v124, v151
	v_mul_f32_e32 v120, v124, v120
	v_mul_f32_e32 v124, v125, v154
	v_mul_f32_e32 v125, 0xbfb8aa3b, v126
	v_exp_f32_e32 v125, v125
	v_mul_f32_e32 v151, 0xbfb8aa3b, v127
	v_exp_f32_e32 v151, v151
	v_mul_f32_e32 v121, v124, v121
	v_add_f32_e32 v124, 1.0, v125
	v_rcp_f32_e32 v124, v124
	v_add_f32_e32 v125, 1.0, v151
	v_rcp_f32_e32 v125, v125
	v_cvt_pk_bf16_f32 v120, v120, v121
	v_mul_f32_e32 v121, v126, v124
	v_mul_f32_e32 v124, 0xbfb8aa3b, v116
	v_mul_f32_e32 v121, v121, v122
	v_mul_f32_e32 v122, v127, v125
	v_exp_f32_e32 v124, v124
	v_mul_f32_e32 v125, 0xbfb8aa3b, v117
	v_exp_f32_e32 v125, v125
	v_mul_f32_e32 v122, v122, v123
	v_add_f32_e32 v123, 1.0, v124
	v_rcp_f32_e32 v123, v123
	v_add_f32_e32 v124, 1.0, v125
	v_rcp_f32_e32 v124, v124
	v_cvt_pk_bf16_f32 v121, v121, v122
	v_mul_f32_e32 v116, v116, v123
	v_mul_f32_e32 v112, v116, v112
	v_mul_f32_e32 v116, v117, v124
	v_mul_f32_e32 v117, 0xbfb8aa3b, v118
	v_exp_f32_e32 v117, v117
	v_mul_f32_e32 v122, 0xbfb8aa3b, v119
	v_exp_f32_e32 v122, v122
	v_mul_f32_e32 v113, v116, v113
	v_add_f32_e32 v116, 1.0, v117
	v_rcp_f32_e32 v116, v116
	v_add_f32_e32 v117, 1.0, v122
	v_rcp_f32_e32 v117, v117
	v_cvt_pk_bf16_f32 v122, v112, v113
	v_mul_f32_e32 v112, v118, v116
	v_mul_f32_e32 v118, 0xbfb8aa3b, v108
	v_mul_f32_e32 v113, v119, v117
	v_exp_f32_e32 v118, v118
	v_mul_f32_e32 v119, 0xbfb8aa3b, v109
	v_exp_f32_e32 v119, v119
	v_mul_f32_e32 v112, v112, v114
	v_add_f32_e32 v118, 1.0, v118
	v_rcp_f32_e32 v118, v118
	v_add_f32_e32 v119, 1.0, v119
	v_rcp_f32_e32 v119, v119
	v_mul_f32_e32 v113, v113, v115
	v_cvt_pk_bf16_f32 v123, v112, v113
	v_mov_b64_e32 v[112:113], s[82:83]
	v_mad_i64_i32 v[116:117], s[14:15], v150, s42, v[112:113]
	v_lshlrev_b64 v[114:115], 1, v[152:153]
	v_mul_f32_e32 v108, v108, v118
	v_lshl_add_u64 v[116:117], v[116:117], 0, v[114:115]
	v_mul_f32_e32 v104, v108, v104
	v_mul_f32_e32 v108, v109, v119
	v_mul_f32_e32 v109, 0xbfb8aa3b, v110
	global_store_dwordx4 v[116:117], v[120:123], off
	v_exp_f32_e32 v109, v109
	v_mul_f32_e32 v116, 0xbfb8aa3b, v111
	v_exp_f32_e32 v116, v116
	v_mul_f32_e32 v105, v108, v105
	v_add_f32_e32 v108, 1.0, v109
	v_rcp_f32_e32 v108, v108
	v_add_f32_e32 v109, 1.0, v116
	v_rcp_f32_e32 v109, v109
	v_cvt_pk_bf16_f32 v104, v104, v105
	v_mul_f32_e32 v105, v110, v108
	v_mul_f32_e32 v108, 0xbfb8aa3b, v100
	v_mul_f32_e32 v105, v105, v106
	v_mul_f32_e32 v106, v111, v109
	v_exp_f32_e32 v108, v108
	v_mul_f32_e32 v109, 0xbfb8aa3b, v101
	v_exp_f32_e32 v109, v109
	v_mul_f32_e32 v106, v106, v107
	v_add_f32_e32 v107, 1.0, v108
	v_rcp_f32_e32 v107, v107
	v_add_f32_e32 v108, 1.0, v109
	v_rcp_f32_e32 v108, v108
	v_cvt_pk_bf16_f32 v105, v105, v106
	v_mul_f32_e32 v100, v100, v107
	v_mul_f32_e32 v96, v100, v96
	v_mul_f32_e32 v100, v101, v108
	v_mul_f32_e32 v101, 0xbfb8aa3b, v102
	v_exp_f32_e32 v101, v101
	v_mul_f32_e32 v106, 0xbfb8aa3b, v103
	v_exp_f32_e32 v106, v106
	v_mul_f32_e32 v97, v100, v97
	v_add_f32_e32 v100, 1.0, v101
	v_rcp_f32_e32 v100, v100
	v_add_f32_e32 v101, 1.0, v106
	v_rcp_f32_e32 v101, v101
	v_cvt_pk_bf16_f32 v106, v96, v97
	v_mul_f32_e32 v96, v102, v100
	v_mul_f32_e32 v96, v96, v98
	v_mul_f32_e32 v97, v103, v101
	v_mul_f32_e32 v98, 0xbfb8aa3b, v92
	v_mul_f32_e32 v97, v97, v99
	v_exp_f32_e32 v98, v98
	v_mul_f32_e32 v99, 0xbfb8aa3b, v93
	v_exp_f32_e32 v99, v99
	v_cvt_pk_bf16_f32 v107, v96, v97
	v_add_f32_e32 v98, 1.0, v98
	v_rcp_f32_e32 v98, v98
	v_add_f32_e32 v99, 1.0, v99
	v_rcp_f32_e32 v99, v99
	v_add_u32_e32 v96, 16, v150
	v_mad_i64_i32 v[96:97], s[14:15], v96, s42, v[112:113]
	v_mul_f32_e32 v92, v92, v98
	v_lshl_add_u64 v[96:97], v[96:97], 0, v[114:115]
	v_mul_f32_e32 v88, v92, v88
	v_mul_f32_e32 v92, v93, v99
	v_mul_f32_e32 v93, 0xbfb8aa3b, v94
	global_store_dwordx4 v[96:97], v[104:107], off
	v_exp_f32_e32 v93, v93
	v_mul_f32_e32 v96, 0xbfb8aa3b, v95
	v_exp_f32_e32 v96, v96
	v_mul_f32_e32 v89, v92, v89
	v_add_f32_e32 v92, 1.0, v93
	v_rcp_f32_e32 v92, v92
	v_add_f32_e32 v93, 1.0, v96
	v_rcp_f32_e32 v93, v93
	v_cvt_pk_bf16_f32 v88, v88, v89
	v_mul_f32_e32 v89, v94, v92
	v_mul_f32_e32 v92, 0xbfb8aa3b, v84
	v_mul_f32_e32 v89, v89, v90
	v_mul_f32_e32 v90, v95, v93
	v_exp_f32_e32 v92, v92
	v_mul_f32_e32 v93, 0xbfb8aa3b, v85
	v_exp_f32_e32 v93, v93
	v_mul_f32_e32 v90, v90, v91
	v_add_f32_e32 v91, 1.0, v92
	v_rcp_f32_e32 v91, v91
	v_add_f32_e32 v92, 1.0, v93
	v_rcp_f32_e32 v92, v92
	v_cvt_pk_bf16_f32 v89, v89, v90
	v_mul_f32_e32 v84, v84, v91
	v_mul_f32_e32 v80, v84, v80
	v_mul_f32_e32 v84, v85, v92
	v_mul_f32_e32 v85, 0xbfb8aa3b, v86
	v_exp_f32_e32 v85, v85
	v_mul_f32_e32 v90, 0xbfb8aa3b, v87
	v_exp_f32_e32 v90, v90
	v_mul_f32_e32 v81, v84, v81
	v_add_f32_e32 v84, 1.0, v85
	v_rcp_f32_e32 v84, v84
	v_add_f32_e32 v85, 1.0, v90
	v_rcp_f32_e32 v85, v85
	v_cvt_pk_bf16_f32 v90, v80, v81
	v_mul_f32_e32 v80, v86, v84
	v_mul_f32_e32 v80, v80, v82
	v_mul_f32_e32 v81, v87, v85
	v_mul_f32_e32 v82, 0xbfb8aa3b, v76
	v_mul_f32_e32 v81, v81, v83
	v_exp_f32_e32 v82, v82
	v_mul_f32_e32 v83, 0xbfb8aa3b, v77
	v_exp_f32_e32 v83, v83
	v_cvt_pk_bf16_f32 v91, v80, v81
	v_add_f32_e32 v82, 1.0, v82
	v_rcp_f32_e32 v82, v82
	v_add_f32_e32 v83, 1.0, v83
	v_rcp_f32_e32 v83, v83
; __device__ __forceinline__ unsigned cvt_pk_bf16(float lo, float hi) { unsigned r; asm volatile("v_cvt_pk_bf16_f32 %0, %1, %2" : "=v"(r) : "v"(lo), "v"(hi)); return r; }
; __device__ __forceinline__ float silu_f(float a) { return a * __builtin_amdgcn_rcpf(1.0f + __expf(-a)); }
;     __device__ __forceinline__ void operator()(const AccT& acc, const Unit& u, int wr, int wc, int fr, int fq) const {
;     ...
;         for (int ai = 0; ai < 2; ++ai)
; #pragma unroll
;             for (int m = 0; m < 4; ++m) {
;                 const f32x4 a0 = acc[ai][0][m][0], a1 = acc[ai][0][m][1], b0 = acc[ai][1][m][0], b1 = acc[ai][1][m][1];
;                 u32x4 w;
;                 w.x = cvt_pk_bf16(silu_f(a0[0]) * b0[0], silu_f(a0[1]) * b0[1]); w.y = cvt_pk_bf16(silu_f(a0[2]) * b0[2], silu_f(a0[3]) * b0[3]);
;                 w.z = cvt_pk_bf16(silu_f(a1[0]) * b1[0], silu_f(a1[1]) * b1[1]); w.w = cvt_pk_bf16(silu_f(a1[2]) * b1[2], silu_f(a1[3]) * b1[3]);
;                 *(u32x4*)(H + (size_t)(row0 + ai * 128 + m * 16) * DFF + hc0) = w;
;             }
	v_add_u32_e32 v80, 32, v150
	v_mad_i64_i32 v[80:81], s[14:15], v80, s42, v[112:113]
	v_mul_f32_e32 v76, v76, v82
	v_lshl_add_u64 v[80:81], v[80:81], 0, v[114:115]
	v_mul_f32_e32 v72, v76, v72
	v_mul_f32_e32 v76, v77, v83
	v_mul_f32_e32 v77, 0xbfb8aa3b, v78
	global_store_dwordx4 v[80:81], v[88:91], off
	v_exp_f32_e32 v77, v77
	v_mul_f32_e32 v80, 0xbfb8aa3b, v79
	v_exp_f32_e32 v80, v80
	v_mul_f32_e32 v73, v76, v73
	v_add_f32_e32 v76, 1.0, v77
	v_rcp_f32_e32 v76, v76
	v_add_f32_e32 v77, 1.0, v80
	v_rcp_f32_e32 v77, v77
	v_cvt_pk_bf16_f32 v72, v72, v73
	v_mul_f32_e32 v73, v78, v76
	v_mul_f32_e32 v76, 0xbfb8aa3b, v68
	v_mul_f32_e32 v73, v73, v74
	v_mul_f32_e32 v74, v79, v77
	v_exp_f32_e32 v76, v76
	v_mul_f32_e32 v77, 0xbfb8aa3b, v69
	v_exp_f32_e32 v77, v77
	v_mul_f32_e32 v74, v74, v75
	v_add_f32_e32 v75, 1.0, v76
	v_rcp_f32_e32 v75, v75
	v_add_f32_e32 v76, 1.0, v77
	v_rcp_f32_e32 v76, v76
	v_cvt_pk_bf16_f32 v73, v73, v74
	v_mul_f32_e32 v68, v68, v75
	v_mul_f32_e32 v64, v68, v64
	v_mul_f32_e32 v68, v69, v76
	v_mul_f32_e32 v69, 0xbfb8aa3b, v70
	v_exp_f32_e32 v69, v69
	v_mul_f32_e32 v74, 0xbfb8aa3b, v71
	v_exp_f32_e32 v74, v74
	v_mul_f32_e32 v65, v68, v65
	v_add_f32_e32 v68, 1.0, v69
	v_rcp_f32_e32 v68, v68
	v_add_f32_e32 v69, 1.0, v74
	v_rcp_f32_e32 v69, v69
	v_cvt_pk_bf16_f32 v74, v64, v65
	v_mul_f32_e32 v64, v70, v68
	v_mul_f32_e32 v64, v64, v66
	v_mul_f32_e32 v65, v71, v69
	v_mul_f32_e32 v66, 0xbfb8aa3b, v60
	v_mul_f32_e32 v65, v65, v67
	v_exp_f32_e32 v66, v66
	v_mul_f32_e32 v67, 0xbfb8aa3b, v61
	v_cvt_pk_bf16_f32 v75, v64, v65
	v_add_u32_e32 v64, 48, v150
	v_exp_f32_e32 v67, v67
	v_mad_i64_i32 v[64:65], s[14:15], v64, s42, v[112:113]
	v_lshl_add_u64 v[64:65], v[64:65], 0, v[114:115]
	global_store_dwordx4 v[64:65], v[72:75], off
	v_add_f32_e32 v64, 1.0, v66
	v_rcp_f32_e32 v64, v64
	v_add_f32_e32 v65, 1.0, v67
	v_rcp_f32_e32 v65, v65
	v_add_u32_e32 v66, 0x80, v150
	v_mul_f32_e32 v60, v60, v64
	v_mul_f32_e32 v52, v60, v52
	v_mul_f32_e32 v60, v61, v65
	v_mul_f32_e32 v61, 0xbfb8aa3b, v62
	v_exp_f32_e32 v61, v61
	v_mul_f32_e32 v64, 0xbfb8aa3b, v63
	v_exp_f32_e32 v64, v64
	v_mul_f32_e32 v53, v60, v53
	v_add_f32_e32 v60, 1.0, v61
	v_rcp_f32_e32 v60, v60
	v_add_f32_e32 v61, 1.0, v64
	v_rcp_f32_e32 v61, v61
	v_cvt_pk_bf16_f32 v52, v52, v53
	v_mul_f32_e32 v53, v62, v60
	v_mul_f32_e32 v60, 0xbfb8aa3b, v56
	v_exp_f32_e32 v60, v60
	v_mul_f32_e32 v53, v53, v54
	v_mul_f32_e32 v54, v63, v61
	v_mul_f32_e32 v61, 0xbfb8aa3b, v57
	v_exp_f32_e32 v61, v61
	v_mul_f32_e32 v54, v54, v55
	v_add_f32_e32 v55, 1.0, v60
	v_rcp_f32_e32 v55, v55
	v_add_f32_e32 v60, 1.0, v61
	v_rcp_f32_e32 v60, v60
	v_cvt_pk_bf16_f32 v53, v53, v54
	v_mul_f32_e32 v54, v56, v55
	v_mul_f32_e32 v55, 0xbfb8aa3b, v58
	v_exp_f32_e32 v55, v55
	v_mul_f32_e32 v56, 0xbfb8aa3b, v59
	v_exp_f32_e32 v56, v56
	v_mul_f32_e32 v48, v54, v48
	v_mul_f32_e32 v54, v57, v60
	v_mul_f32_e32 v49, v54, v49
	v_add_f32_e32 v54, 1.0, v55
	v_rcp_f32_e32 v55, v54
	v_add_f32_e32 v54, 1.0, v56
	v_rcp_f32_e32 v56, v54
	v_cvt_pk_bf16_f32 v54, v48, v49
	v_mul_f32_e32 v48, v58, v55
	v_mul_f32_e32 v48, v48, v50
	v_mul_f32_e32 v49, v59, v56
	v_mul_f32_e32 v50, 0xbfb8aa3b, v44
	v_mul_f32_e32 v49, v49, v51
	v_exp_f32_e32 v50, v50
	v_mul_f32_e32 v51, 0xbfb8aa3b, v45
	v_exp_f32_e32 v51, v51
	v_cvt_pk_bf16_f32 v55, v48, v49
	v_add_f32_e32 v50, 1.0, v50
	v_rcp_f32_e32 v50, v50
	v_add_f32_e32 v51, 1.0, v51
	v_rcp_f32_e32 v51, v51
	v_mad_i64_i32 v[48:49], s[14:15], v66, s42, v[112:113]
	v_mul_f32_e32 v44, v44, v50
	v_mul_f32_e32 v36, v44, v36
	v_mul_f32_e32 v44, v45, v51
	v_mul_f32_e32 v45, 0xbfb8aa3b, v46
	v_exp_f32_e32 v45, v45
	v_lshl_add_u64 v[48:49], v[48:49], 0, v[114:115]
	global_store_dwordx4 v[48:49], v[52:55], off
	v_mul_f32_e32 v48, 0xbfb8aa3b, v47
	v_exp_f32_e32 v48, v48
	v_mul_f32_e32 v37, v44, v37
	v_add_f32_e32 v44, 1.0, v45
	v_rcp_f32_e32 v44, v44
	v_add_f32_e32 v45, 1.0, v48
	v_rcp_f32_e32 v45, v45
	v_cvt_pk_bf16_f32 v36, v36, v37
	v_mul_f32_e32 v37, v46, v44
	v_mul_f32_e32 v44, 0xbfb8aa3b, v40
	v_exp_f32_e32 v44, v44
	v_mul_f32_e32 v37, v37, v38
	v_mul_f32_e32 v38, v47, v45
	v_mul_f32_e32 v45, 0xbfb8aa3b, v41
	v_exp_f32_e32 v45, v45
	v_mul_f32_e32 v38, v38, v39
	v_add_f32_e32 v39, 1.0, v44
	v_rcp_f32_e32 v39, v39
	v_add_f32_e32 v44, 1.0, v45
; __device__ __forceinline__ unsigned cvt_pk_bf16(float lo, float hi) { unsigned r; asm volatile("v_cvt_pk_bf16_f32 %0, %1, %2" : "=v"(r) : "v"(lo), "v"(hi)); return r; }
; __device__ __forceinline__ float silu_f(float a) { return a * __builtin_amdgcn_rcpf(1.0f + __expf(-a)); }
; template <class Epi, class Sched>
; __device__ __forceinline__ void gemm_phase(LAS unsigned char* lds, const Gemm g, const Sched& S, const Epi& E) {
;     ...
;         E(acc, cur, wr, wc, fr, fq);
;         if (!has_next) break;
; #pragma unroll
;         for (int a = 0; a < 2; ++a)
; #pragma unroll
;             for (int b = 0; b < 2; ++b)
; #pragma unroll
;                 for (int m = 0; m < 4; ++m)
; #pragma unroll
;                     for (int n = 0; n < 2; ++n) acc[a][b][m][n] = (f32x4){0.f, 0.f, 0.f, 0.f};
;         cur = nxt; cA = nA; cB = nB; ++ui;
;     __device__ __forceinline__ void operator()(const AccT& acc, const Unit& u, int wr, int wc, int fr, int fq) const {
;     ...
;         for (int ai = 0; ai < 2; ++ai)
; #pragma unroll
;             for (int m = 0; m < 4; ++m) {
;                 const f32x4 a0 = acc[ai][0][m][0], a1 = acc[ai][0][m][1], b0 = acc[ai][1][m][0], b1 = acc[ai][1][m][1];
;                 u32x4 w;
;                 w.x = cvt_pk_bf16(silu_f(a0[0]) * b0[0], silu_f(a0[1]) * b0[1]); w.y = cvt_pk_bf16(silu_f(a0[2]) * b0[2], silu_f(a0[3]) * b0[3]);
;                 w.z = cvt_pk_bf16(silu_f(a1[0]) * b1[0], silu_f(a1[1]) * b1[1]); w.w = cvt_pk_bf16(silu_f(a1[2]) * b1[2], silu_f(a1[3]) * b1[3]);
;                 *(u32x4*)(H + (size_t)(row0 + ai * 128 + m * 16) * DFF + hc0) = w;
;             }
	v_rcp_f32_e32 v44, v44
	v_cvt_pk_bf16_f32 v37, v37, v38
	v_mul_f32_e32 v38, v40, v39
	v_mul_f32_e32 v39, 0xbfb8aa3b, v42
	v_exp_f32_e32 v39, v39
	v_mul_f32_e32 v40, 0xbfb8aa3b, v43
	v_exp_f32_e32 v40, v40
	v_mul_f32_e32 v32, v38, v32
	v_mul_f32_e32 v38, v41, v44
	v_mul_f32_e32 v33, v38, v33
	v_add_f32_e32 v38, 1.0, v39
	v_rcp_f32_e32 v39, v38
	v_add_f32_e32 v38, 1.0, v40
	v_rcp_f32_e32 v40, v38
	v_cvt_pk_bf16_f32 v38, v32, v33
	v_mul_f32_e32 v32, v42, v39
	v_mul_f32_e32 v32, v32, v34
	v_mul_f32_e32 v33, v43, v40
	v_mul_f32_e32 v34, 0xbfb8aa3b, v28
	v_mul_f32_e32 v33, v33, v35
	v_exp_f32_e32 v34, v34
	v_mul_f32_e32 v35, 0xbfb8aa3b, v29
	v_exp_f32_e32 v35, v35
	v_cvt_pk_bf16_f32 v39, v32, v33
	v_add_f32_e32 v34, 1.0, v34
	v_rcp_f32_e32 v34, v34
	v_add_f32_e32 v35, 1.0, v35
	v_rcp_f32_e32 v35, v35
	v_add_u32_e32 v32, 0x90, v150
	v_mul_f32_e32 v28, v28, v34
	v_mul_f32_e32 v20, v28, v20
	v_mul_f32_e32 v28, v29, v35
	v_mul_f32_e32 v29, 0xbfb8aa3b, v30
	v_exp_f32_e32 v29, v29
	v_mad_i64_i32 v[32:33], s[14:15], v32, s42, v[112:113]
	v_lshl_add_u64 v[32:33], v[32:33], 0, v[114:115]
	global_store_dwordx4 v[32:33], v[36:39], off
	v_mul_f32_e32 v32, 0xbfb8aa3b, v31
	v_exp_f32_e32 v32, v32
	v_mul_f32_e32 v21, v28, v21
	v_add_f32_e32 v28, 1.0, v29
	v_rcp_f32_e32 v28, v28
	v_add_f32_e32 v29, 1.0, v32
	v_rcp_f32_e32 v29, v29
	v_cvt_pk_bf16_f32 v20, v20, v21
	v_mul_f32_e32 v21, v30, v28
	v_mul_f32_e32 v28, 0xbfb8aa3b, v24
	v_exp_f32_e32 v28, v28
	v_mul_f32_e32 v21, v21, v22
	v_mul_f32_e32 v22, v31, v29
	v_mul_f32_e32 v29, 0xbfb8aa3b, v25
	v_exp_f32_e32 v29, v29
	v_mul_f32_e32 v22, v22, v23
	v_add_f32_e32 v23, 1.0, v28
	v_rcp_f32_e32 v23, v23
	v_add_f32_e32 v28, 1.0, v29
	v_rcp_f32_e32 v28, v28
	v_cvt_pk_bf16_f32 v21, v21, v22
	v_mul_f32_e32 v22, v24, v23
	v_mul_f32_e32 v23, 0xbfb8aa3b, v26
	v_exp_f32_e32 v23, v23
	v_mul_f32_e32 v24, 0xbfb8aa3b, v27
	v_exp_f32_e32 v24, v24
	v_mul_f32_e32 v16, v22, v16
	v_mul_f32_e32 v22, v25, v28
	v_mul_f32_e32 v17, v22, v17
	v_add_f32_e32 v22, 1.0, v23
	v_rcp_f32_e32 v23, v22
	v_add_f32_e32 v22, 1.0, v24
	v_rcp_f32_e32 v24, v22
	v_cvt_pk_bf16_f32 v22, v16, v17
	v_mul_f32_e32 v16, v26, v23
	v_mul_f32_e32 v16, v16, v18
	v_mul_f32_e32 v17, v27, v24
	v_mul_f32_e32 v18, 0xbfb8aa3b, v12
	v_mul_f32_e32 v17, v17, v19
	v_exp_f32_e32 v18, v18
	v_mul_f32_e32 v19, 0xbfb8aa3b, v13
	v_exp_f32_e32 v19, v19
	v_cvt_pk_bf16_f32 v23, v16, v17
	v_add_f32_e32 v18, 1.0, v18
	v_rcp_f32_e32 v18, v18
	v_add_f32_e32 v19, 1.0, v19
	v_rcp_f32_e32 v19, v19
	v_add_u32_e32 v16, 0xa0, v150
	v_mul_f32_e32 v12, v12, v18
	v_mul_f32_e32 v4, v12, v4
	v_mul_f32_e32 v12, v13, v19
	v_mul_f32_e32 v13, 0xbfb8aa3b, v14
	v_exp_f32_e32 v13, v13
	v_mad_i64_i32 v[16:17], s[14:15], v16, s42, v[112:113]
	v_lshl_add_u64 v[16:17], v[16:17], 0, v[114:115]
	global_store_dwordx4 v[16:17], v[20:23], off
	v_mul_f32_e32 v16, 0xbfb8aa3b, v15
	v_exp_f32_e32 v16, v16
	v_mul_f32_e32 v5, v12, v5
	v_add_f32_e32 v12, 1.0, v13
	v_rcp_f32_e32 v12, v12
	v_add_f32_e32 v13, 1.0, v16
	v_rcp_f32_e32 v13, v13
	v_cvt_pk_bf16_f32 v4, v4, v5
	v_mul_f32_e32 v5, v14, v12
	v_mul_f32_e32 v12, 0xbfb8aa3b, v8
	v_exp_f32_e32 v12, v12
	v_mul_f32_e32 v5, v5, v6
	v_mul_f32_e32 v6, v15, v13
	v_mul_f32_e32 v13, 0xbfb8aa3b, v9
	v_exp_f32_e32 v13, v13
	v_mul_f32_e32 v6, v6, v7
	v_add_f32_e32 v7, 1.0, v12
	v_rcp_f32_e32 v7, v7
	v_add_f32_e32 v12, 1.0, v13
	v_rcp_f32_e32 v12, v12
	v_cvt_pk_bf16_f32 v5, v5, v6
	v_mul_f32_e32 v6, v8, v7
	v_mul_f32_e32 v7, 0xbfb8aa3b, v10
	v_exp_f32_e32 v7, v7
	v_mul_f32_e32 v8, 0xbfb8aa3b, v11
	v_exp_f32_e32 v8, v8
	v_mul_f32_e32 v0, v6, v0
	v_mul_f32_e32 v6, v9, v12
	v_mul_f32_e32 v1, v6, v1
	v_add_f32_e32 v6, 1.0, v7
	v_rcp_f32_e32 v7, v6
	v_add_f32_e32 v6, 1.0, v8
	v_rcp_f32_e32 v8, v6
	v_cvt_pk_bf16_f32 v6, v0, v1
	v_mul_f32_e32 v0, v10, v7
	v_mul_f32_e32 v0, v0, v2
	v_mul_f32_e32 v1, v11, v8
	v_mul_f32_e32 v1, v1, v3
	v_cvt_pk_bf16_f32 v7, v0, v1
	v_add_u32_e32 v0, 0xb0, v150
	v_mad_i64_i32 v[0:1], s[14:15], v0, s42, v[112:113]
	v_lshl_add_u64 v[0:1], v[0:1], 0, v[114:115]
	s_and_b64 vcc, exec, s[2:3]
	s_mov_b32 s43, s4
	s_mov_b32 s12, s6
	s_mov_b64 s[18:19], s[10:11]
	s_mov_b64 s[14:15], s[8:9]
	global_store_dwordx4 v[0:1], v[4:7], off
	s_barrier
	s_cbranch_vccz .LBB0_232

; #define PG8_STAGE(bufoff, gbase, voff) do { _Pragma("unroll") for (int _i = 0; _i < 2; ++_i) \
;         __builtin_amdgcn_global_load_lds((const unsigned*)((const char*)(gbase) + (voff)[_i]), (LAS unsigned*)(lds + (bufoff) + ldsw + _i * 8192), 16, 0, 0); } while (0)
; #define PG8_LDA(dst, b, h) do { _Pragma("unroll") for (int m = 0; m < 4; ++m) _Pragma("unroll") for (int k = 0; k < 2; ++k) dst[m][k] = *(const LAS bf16x8*)(lds + PG8_SA(b, h) + aoff + m * 2048 + k * 1024); } while (0)
; #define PG8_LDB(dst, b, h) do { _Pragma("unroll") for (int n = 0; n < 2; ++n) _Pragma("unroll") for (int k = 0; k < 2; ++k) dst[n][k] = *(const LAS bf16x8*)(lds + PG8_SB(b, h) + boff + n * 2048 + k * 1024); } while (0)
; #define PG8_MMA(ai, bj, At, Bt) do { __builtin_amdgcn_s_setprio(1); _Pragma("unroll") for (int m = 0; m < 4; ++m) _Pragma("unroll") for (int n = 0; n < 2; ++n) _Pragma("unroll") for (int k = 0; k < 2; ++k) \
;         acc[ai][bj][m][n] = __builtin_amdgcn_mfma_f32_16x16x32_bf16(Bt[n][k], At[m][k], acc[ai][bj][m][n], 0, 0, 0); __builtin_amdgcn_s_setprio(0); } while (0)
; #define PG8_WAIT_V(n) asm volatile("s_waitcnt vmcnt(" #n ")" ::: "memory")
; #define PG8_WAIT_L(n) asm volatile("s_waitcnt lgkmcnt(" #n ")" ::: "memory")
; #define PG8_BAR __builtin_amdgcn_s_barrier()
; #define PG8_SCHED __builtin_amdgcn_sched_barrier(0)
; template <class Epi, class Sched>
; __device__ __forceinline__ void gemm_phase(LAS unsigned char* lds, const Gemm g, const Sched& S, const Epi& E) {
;     ...
;             PG8_LDB(B0, 0, 0); PG8_SCHED; PG8_LDA(At, 0, 0); PG8_STAGE(PG8_SA(1, 1), a1 + hstep, voffA);
;             PG8_WAIT_L(8); PG8_BAR; PG8_WAIT_L(0); PG8_MMA(0, 0, At, B0); PG8_BAR; PG8_SCHED;
;             PG8_LDB(B1, 0, 1); PG8_STAGE(PG8_SB(0, 0), b2, voffB);
;             PG8_BAR; PG8_WAIT_L(0); PG8_MMA(0, 1, At, B1); PG8_BAR;
;             PG8_LDA(At, 0, 1); PG8_STAGE(PG8_SA(0, 0), a2, voffA);
;             PG8_BAR; PG8_WAIT_L(0); PG8_MMA(1, 0, At, B0); PG8_BAR; PG8_SCHED;
;             PG8_STAGE(PG8_SB(0, 1), b2 + hstep, voffB);
;             PG8_WAIT_V(6); PG8_BAR; PG8_MMA(1, 1, At, B1); PG8_BAR;
.LBB0_1021:
	ds_read_b128 v[150:153], v147
	ds_read_b128 v[154:157], v147 offset:1024
	ds_read_b128 v[158:161], v147 offset:2048
	ds_read_b128 v[162:165], v147 offset:3072
	s_add_u32 s18, s16, 0xfffc0080
	s_addc_u32 s19, s17, -1
	s_cmp_eq_u32 s46, 12
	s_cselect_b32 s21, s7, s19
	s_cselect_b32 s20, s42, s18
	s_cselect_b32 s19, s5, s45
	s_cselect_b32 s18, s43, s44
	s_add_i32 m0, s15, 0xc000
	ds_read_b128 v[166:169], v148
	ds_read_b128 v[170:173], v148 offset:1024
	ds_read_b128 v[174:177], v148 offset:2048
	ds_read_b128 v[178:181], v148 offset:3072
	ds_read_b128 v[182:185], v148 offset:4096
	ds_read_b128 v[186:189], v148 offset:5120
	ds_read_b128 v[190:193], v148 offset:6144
	ds_read_b128 v[194:197], v148 offset:7168
	global_load_lds_dwordx4 v136, s[16:17]
	s_add_i32 m0, s15, 0xe000
	s_nop 0
	global_load_lds_dwordx4 v138, s[16:17]
	s_waitcnt lgkmcnt(8)
	s_waitcnt vmcnt(8)
	s_setprio 1
	s_barrier
	s_waitcnt lgkmcnt(0)
	v_mfma_f32_16x16x32_bf16 v[124:127], v[150:153], v[166:169], v[124:127]
	v_mfma_f32_16x16x32_bf16 v[116:119], v[158:161], v[166:169], v[116:119]
	v_mfma_f32_16x16x32_bf16 v[108:111], v[150:153], v[174:177], v[108:111]
	v_mfma_f32_16x16x32_bf16 v[100:103], v[158:161], v[174:177], v[100:103]
	v_mfma_f32_16x16x32_bf16 v[92:95], v[150:153], v[182:185], v[92:95]
	v_mfma_f32_16x16x32_bf16 v[84:87], v[158:161], v[182:185], v[84:87]
	v_mfma_f32_16x16x32_bf16 v[76:79], v[150:153], v[190:193], v[76:79]
	v_mfma_f32_16x16x32_bf16 v[68:71], v[158:161], v[190:193], v[68:71]
	v_mfma_f32_16x16x32_bf16 v[124:127], v[154:157], v[170:173], v[124:127]
	v_mfma_f32_16x16x32_bf16 v[116:119], v[162:165], v[170:173], v[116:119]
	v_mfma_f32_16x16x32_bf16 v[108:111], v[154:157], v[178:181], v[108:111]
	v_mfma_f32_16x16x32_bf16 v[100:103], v[162:165], v[178:181], v[100:103]
	v_mfma_f32_16x16x32_bf16 v[92:95], v[154:157], v[186:189], v[92:95]
	v_mfma_f32_16x16x32_bf16 v[84:87], v[162:165], v[186:189], v[84:87]
	v_mfma_f32_16x16x32_bf16 v[76:79], v[154:157], v[194:197], v[76:79]
	v_mfma_f32_16x16x32_bf16 v[68:71], v[162:165], v[194:197], v[68:71]
	s_barrier
	s_setprio 0
	s_add_i32 s47, s38, s25
	s_mov_b32 m0, s47
	ds_read_b128 v[202:205], v149
	ds_read_b128 v[206:209], v149 offset:1024
	ds_read_b128 v[210:213], v149 offset:2048
	ds_read_b128 v[214:217], v149 offset:3072
	global_load_lds_dwordx4 v132, s[18:19]
	s_add_i32 m0, s47, 0x2000
	s_nop 0
	global_load_lds_dwordx4 v128, s[18:19]
	s_waitcnt vmcnt(8)
	s_setprio 1
	s_barrier
	s_waitcnt lgkmcnt(0)
	v_mfma_f32_16x16x32_bf16 v[120:123], v[202:205], v[166:169], v[120:123]
	v_mfma_f32_16x16x32_bf16 v[112:115], v[210:213], v[166:169], v[112:115]
	v_mfma_f32_16x16x32_bf16 v[104:107], v[202:205], v[174:177], v[104:107]
	v_mfma_f32_16x16x32_bf16 v[96:99], v[210:213], v[174:177], v[96:99]
	v_mfma_f32_16x16x32_bf16 v[88:91], v[202:205], v[182:185], v[88:91]
	v_mfma_f32_16x16x32_bf16 v[80:83], v[210:213], v[182:185], v[80:83]
	v_mfma_f32_16x16x32_bf16 v[72:75], v[202:205], v[190:193], v[72:75]
	v_mfma_f32_16x16x32_bf16 v[64:67], v[210:213], v[190:193], v[64:67]
	v_mfma_f32_16x16x32_bf16 v[120:123], v[206:209], v[170:173], v[120:123]
	v_mfma_f32_16x16x32_bf16 v[112:115], v[214:217], v[170:173], v[112:115]
	v_mfma_f32_16x16x32_bf16 v[104:107], v[206:209], v[178:181], v[104:107]
	v_mfma_f32_16x16x32_bf16 v[96:99], v[214:217], v[178:181], v[96:99]
	v_mfma_f32_16x16x32_bf16 v[88:91], v[206:209], v[186:189], v[88:91]
	v_mfma_f32_16x16x32_bf16 v[80:83], v[214:217], v[186:189], v[80:83]
	v_mfma_f32_16x16x32_bf16 v[72:75], v[206:209], v[194:197], v[72:75]
	v_mfma_f32_16x16x32_bf16 v[64:67], v[214:217], v[194:197], v[64:67]
	s_barrier
	s_setprio 0
	s_mov_b32 m0, s15
	v_lshl_add_u64 v[220:221], s[20:21], 0, v[134:135]
	ds_read_b128 v[166:169], v148 offset:16384
	ds_read_b128 v[170:173], v148 offset:17408
	ds_read_b128 v[174:177], v148 offset:18432
	ds_read_b128 v[178:181], v148 offset:19456
	ds_read_b128 v[182:185], v148 offset:20480
	ds_read_b128 v[186:189], v148 offset:21504
	ds_read_b128 v[190:193], v148 offset:22528
	ds_read_b128 v[194:197], v148 offset:23552
	global_load_lds_dwordx4 v134, s[20:21]
	v_lshl_add_u64 v[222:223], s[20:21], 0, v[130:131]
	s_mov_b32 m0, s28
	s_nop 0
	global_load_lds_dwordx4 v130, s[20:21]
	s_setprio 1
	s_barrier
	s_waitcnt lgkmcnt(0)
	v_mfma_f32_16x16x32_bf16 v[60:63], v[150:153], v[166:169], v[60:63]
	v_mfma_f32_16x16x32_bf16 v[56:59], v[158:161], v[166:169], v[56:59]
	v_mfma_f32_16x16x32_bf16 v[44:47], v[150:153], v[174:177], v[44:47]
	v_mfma_f32_16x16x32_bf16 v[40:43], v[158:161], v[174:177], v[40:43]
	v_mfma_f32_16x16x32_bf16 v[28:31], v[150:153], v[182:185], v[28:31]
	v_mfma_f32_16x16x32_bf16 v[24:27], v[158:161], v[182:185], v[24:27]
	v_mfma_f32_16x16x32_bf16 v[12:15], v[150:153], v[190:193], v[12:15]
	v_mfma_f32_16x16x32_bf16 v[8:11], v[158:161], v[190:193], v[8:11]
	v_mfma_f32_16x16x32_bf16 v[60:63], v[154:157], v[170:173], v[60:63]
	v_mfma_f32_16x16x32_bf16 v[56:59], v[162:165], v[170:173], v[56:59]
	v_mfma_f32_16x16x32_bf16 v[44:47], v[154:157], v[178:181], v[44:47]
	v_mfma_f32_16x16x32_bf16 v[40:43], v[162:165], v[178:181], v[40:43]
	v_mfma_f32_16x16x32_bf16 v[28:31], v[154:157], v[186:189], v[28:31]
	v_mfma_f32_16x16x32_bf16 v[24:27], v[162:165], v[186:189], v[24:27]
	v_mfma_f32_16x16x32_bf16 v[12:15], v[154:157], v[194:197], v[12:15]
	v_mfma_f32_16x16x32_bf16 v[8:11], v[162:165], v[194:197], v[8:11]
	s_barrier
	s_setprio 0
	s_add_u32 s48, s18, 0x40000
	s_addc_u32 s49, s19, 0
	s_add_i32 s47, s39, s25
	s_mov_b32 m0, s47
	s_nop 0
	global_load_lds_dwordx4 v132, s[48:49]
	s_add_i32 m0, s47, 0x2000
	s_nop 0
	global_load_lds_dwordx4 v128, s[48:49]
	s_add_u32 s20, s20, 0x40000
	s_addc_u32 s21, s21, 0
	s_mov_b32 m0, s29
	s_nop 0
	global_load_lds_dwordx4 v134, s[20:21]
	s_mov_b32 m0, s30
	s_nop 0
	global_load_lds_dwordx4 v130, s[20:21]
	s_waitcnt vmcnt(10)
	s_setprio 1
	s_barrier
; #define PG8_STAGE(bufoff, gbase, voff) do { _Pragma("unroll") for (int _i = 0; _i < 2; ++_i) \
;         __builtin_amdgcn_global_load_lds((const unsigned*)((const char*)(gbase) + (voff)[_i]), (LAS unsigned*)(lds + (bufoff) + ldsw + _i * 8192), 16, 0, 0); } while (0)
; #define PG8_LDA(dst, b, h) do { _Pragma("unroll") for (int m = 0; m < 4; ++m) _Pragma("unroll") for (int k = 0; k < 2; ++k) dst[m][k] = *(const LAS bf16x8*)(lds + PG8_SA(b, h) + aoff + m * 2048 + k * 1024); } while (0)
; #define PG8_LDB(dst, b, h) do { _Pragma("unroll") for (int n = 0; n < 2; ++n) _Pragma("unroll") for (int k = 0; k < 2; ++k) dst[n][k] = *(const LAS bf16x8*)(lds + PG8_SB(b, h) + boff + n * 2048 + k * 1024); } while (0)
; #define PG8_MMA(ai, bj, At, Bt) do { __builtin_amdgcn_s_setprio(1); _Pragma("unroll") for (int m = 0; m < 4; ++m) _Pragma("unroll") for (int n = 0; n < 2; ++n) _Pragma("unroll") for (int k = 0; k < 2; ++k) \
;         acc[ai][bj][m][n] = __builtin_amdgcn_mfma_f32_16x16x32_bf16(Bt[n][k], At[m][k], acc[ai][bj][m][n], 0, 0, 0); __builtin_amdgcn_s_setprio(0); } while (0)
; #define PG8_WAIT_V(n) asm volatile("s_waitcnt vmcnt(" #n ")" ::: "memory")
; #define PG8_WAIT_L(n) asm volatile("s_waitcnt lgkmcnt(" #n ")" ::: "memory")
; #define PG8_BAR __builtin_amdgcn_s_barrier()
; #define PG8_SCHED __builtin_amdgcn_sched_barrier(0)
; template <class Epi, class Sched>
; __device__ __forceinline__ void gemm_phase(LAS unsigned char* lds, const Gemm g, const Sched& S, const Epi& E) {
;     ...
;             PG8_WAIT_V(6); PG8_BAR; PG8_MMA(1, 1, At, B1); PG8_BAR;
;             PG8_LDB(B0, 1, 0); PG8_SCHED; PG8_LDA(At, 1, 0); PG8_STAGE(PG8_SA(0, 1), a2 + hstep, voffA);
;             PG8_WAIT_L(8); PG8_BAR; PG8_WAIT_L(0); PG8_MMA(0, 0, At, B0); PG8_BAR; PG8_SCHED;
;             PG8_LDB(B1, 1, 1); PG8_STAGE(PG8_SB(1, 0), b3, voffB);
;             PG8_BAR; PG8_WAIT_L(0); PG8_MMA(0, 1, At, B1); PG8_BAR;
;             PG8_LDA(At, 1, 1); PG8_STAGE(PG8_SA(1, 0), a3, voffA);
;             PG8_BAR; PG8_WAIT_L(0); PG8_MMA(1, 0, At, B0); PG8_BAR; PG8_SCHED;
	v_mfma_f32_16x16x32_bf16 v[52:55], v[202:205], v[166:169], v[52:55]
	v_mfma_f32_16x16x32_bf16 v[48:51], v[210:213], v[166:169], v[48:51]
	v_mfma_f32_16x16x32_bf16 v[36:39], v[202:205], v[174:177], v[36:39]
	v_mfma_f32_16x16x32_bf16 v[32:35], v[210:213], v[174:177], v[32:35]
	v_mfma_f32_16x16x32_bf16 v[20:23], v[202:205], v[182:185], v[20:23]
	v_mfma_f32_16x16x32_bf16 v[16:19], v[210:213], v[182:185], v[16:19]
	v_mfma_f32_16x16x32_bf16 v[4:7], v[202:205], v[190:193], v[4:7]
	v_mfma_f32_16x16x32_bf16 v[0:3], v[210:213], v[190:193], v[0:3]
	v_mfma_f32_16x16x32_bf16 v[52:55], v[206:209], v[170:173], v[52:55]
	v_mfma_f32_16x16x32_bf16 v[48:51], v[214:217], v[170:173], v[48:51]
	v_mfma_f32_16x16x32_bf16 v[36:39], v[206:209], v[178:181], v[36:39]
	v_mfma_f32_16x16x32_bf16 v[32:35], v[214:217], v[178:181], v[32:35]
	v_mfma_f32_16x16x32_bf16 v[20:23], v[206:209], v[186:189], v[20:23]
	v_mfma_f32_16x16x32_bf16 v[16:19], v[214:217], v[186:189], v[16:19]
	v_mfma_f32_16x16x32_bf16 v[4:7], v[206:209], v[194:197], v[4:7]
	v_mfma_f32_16x16x32_bf16 v[0:3], v[214:217], v[194:197], v[0:3]
	s_barrier
	s_setprio 0
	s_add_i32 s47, 0, 0x18000
	ds_read_b128 v[150:153], v149 offset:16384
	ds_read_b128 v[154:157], v149 offset:17408
	ds_read_b128 v[158:161], v149 offset:18432
	ds_read_b128 v[162:165], v149 offset:19456
	ds_read_b128 v[166:169], v148 offset:32768
	ds_read_b128 v[170:173], v148 offset:33792
	ds_read_b128 v[174:177], v148 offset:34816
	ds_read_b128 v[178:181], v148 offset:35840
	ds_read_b128 v[182:185], v148 offset:36864
	ds_read_b128 v[186:189], v148 offset:37888
	ds_read_b128 v[190:193], v148 offset:38912
	ds_read_b128 v[194:197], v148 offset:39936
	s_waitcnt lgkmcnt(8)
	s_waitcnt vmcnt(8)
	s_setprio 1
	s_barrier
	s_waitcnt lgkmcnt(0)
	v_mfma_f32_16x16x32_bf16 v[124:127], v[150:153], v[166:169], v[124:127]
	v_mfma_f32_16x16x32_bf16 v[116:119], v[158:161], v[166:169], v[116:119]
	v_mfma_f32_16x16x32_bf16 v[108:111], v[150:153], v[174:177], v[108:111]
	v_mfma_f32_16x16x32_bf16 v[100:103], v[158:161], v[174:177], v[100:103]
	v_mfma_f32_16x16x32_bf16 v[92:95], v[150:153], v[182:185], v[92:95]
	v_mfma_f32_16x16x32_bf16 v[84:87], v[158:161], v[182:185], v[84:87]
	v_mfma_f32_16x16x32_bf16 v[76:79], v[150:153], v[190:193], v[76:79]
	v_mfma_f32_16x16x32_bf16 v[68:71], v[158:161], v[190:193], v[68:71]
	v_mfma_f32_16x16x32_bf16 v[124:127], v[154:157], v[170:173], v[124:127]
	v_mfma_f32_16x16x32_bf16 v[116:119], v[162:165], v[170:173], v[116:119]
	v_mfma_f32_16x16x32_bf16 v[108:111], v[154:157], v[178:181], v[108:111]
	v_mfma_f32_16x16x32_bf16 v[100:103], v[162:165], v[178:181], v[100:103]
	v_mfma_f32_16x16x32_bf16 v[92:95], v[154:157], v[186:189], v[92:95]
	v_mfma_f32_16x16x32_bf16 v[84:87], v[162:165], v[186:189], v[84:87]
	v_mfma_f32_16x16x32_bf16 v[76:79], v[154:157], v[194:197], v[76:79]
	v_mfma_f32_16x16x32_bf16 v[68:71], v[162:165], v[194:197], v[68:71]
	s_barrier
	s_setprio 0
	s_add_i32 s20, 0, 0x1c000
	s_add_i32 s21, s47, s25
	s_add_u32 s0, s18, 0x80
	s_addc_u32 s1, s19, 0
	s_mov_b32 m0, s21
	ds_read_b128 v[202:205], v149 offset:32768
	ds_read_b128 v[206:209], v149 offset:33792
	ds_read_b128 v[210:213], v149 offset:34816
	ds_read_b128 v[214:217], v149 offset:35840
	global_load_lds_dwordx4 v132, s[0:1]
	s_add_i32 m0, s21, 0x2000
	s_nop 0
	global_load_lds_dwordx4 v128, s[0:1]
	s_waitcnt vmcnt(8)
	s_setprio 1
	s_barrier
	s_waitcnt lgkmcnt(0)
	v_mfma_f32_16x16x32_bf16 v[120:123], v[202:205], v[166:169], v[120:123]
	v_mfma_f32_16x16x32_bf16 v[112:115], v[210:213], v[166:169], v[112:115]
	v_mfma_f32_16x16x32_bf16 v[104:107], v[202:205], v[174:177], v[104:107]
	v_mfma_f32_16x16x32_bf16 v[96:99], v[210:213], v[174:177], v[96:99]
	v_mfma_f32_16x16x32_bf16 v[88:91], v[202:205], v[182:185], v[88:91]
	v_mfma_f32_16x16x32_bf16 v[80:83], v[210:213], v[182:185], v[80:83]
	v_mfma_f32_16x16x32_bf16 v[72:75], v[202:205], v[190:193], v[72:75]
	v_mfma_f32_16x16x32_bf16 v[64:67], v[210:213], v[190:193], v[64:67]
	v_mfma_f32_16x16x32_bf16 v[120:123], v[206:209], v[170:173], v[120:123]
	v_mfma_f32_16x16x32_bf16 v[112:115], v[214:217], v[170:173], v[112:115]
	v_mfma_f32_16x16x32_bf16 v[104:107], v[206:209], v[178:181], v[104:107]
	v_mfma_f32_16x16x32_bf16 v[96:99], v[214:217], v[178:181], v[96:99]
	v_mfma_f32_16x16x32_bf16 v[88:91], v[206:209], v[186:189], v[88:91]
	v_mfma_f32_16x16x32_bf16 v[80:83], v[214:217], v[186:189], v[80:83]
	v_mfma_f32_16x16x32_bf16 v[72:75], v[206:209], v[194:197], v[72:75]
	v_mfma_f32_16x16x32_bf16 v[64:67], v[214:217], v[194:197], v[64:67]
	s_barrier
	s_setprio 0
	s_mov_b32 m0, s35
	s_mov_b64 s[0:1], 0x80
	v_lshl_add_u64 v[198:199], v[220:221], 0, s[0:1]
	ds_read_b128 v[166:169], v148 offset:49152
	ds_read_b128 v[170:173], v148 offset:50176
	ds_read_b128 v[174:177], v148 offset:51200
	ds_read_b128 v[178:181], v148 offset:52224
	ds_read_b128 v[182:185], v148 offset:53248
	ds_read_b128 v[186:189], v148 offset:54272
	ds_read_b128 v[190:193], v148 offset:55296
	ds_read_b128 v[194:197], v148 offset:56320
	global_load_lds_dwordx4 v[198:199], off
	v_lshl_add_u64 v[198:199], v[222:223], 0, s[0:1]
	s_mov_b32 m0, s36
	s_nop 0
	global_load_lds_dwordx4 v[198:199], off
	s_setprio 1
	s_barrier
; __device__ __forceinline__ unsigned cvt_pk_bf16(float lo, float hi) { unsigned r; asm volatile("v_cvt_pk_bf16_f32 %0, %1, %2" : "=v"(r) : "v"(lo), "v"(hi)); return r; }
; __device__ __forceinline__ float silu_f(float a) { return a * __builtin_amdgcn_rcpf(1.0f + __expf(-a)); }
; #define PG8_STAGE(bufoff, gbase, voff) do { _Pragma("unroll") for (int _i = 0; _i < 2; ++_i) \
;         __builtin_amdgcn_global_load_lds((const unsigned*)((const char*)(gbase) + (voff)[_i]), (LAS unsigned*)(lds + (bufoff) + ldsw + _i * 8192), 16, 0, 0); } while (0)
; #define PG8_MMA(ai, bj, At, Bt) do { __builtin_amdgcn_s_setprio(1); _Pragma("unroll") for (int m = 0; m < 4; ++m) _Pragma("unroll") for (int n = 0; n < 2; ++n) _Pragma("unroll") for (int k = 0; k < 2; ++k) \
;         acc[ai][bj][m][n] = __builtin_amdgcn_mfma_f32_16x16x32_bf16(Bt[n][k], At[m][k], acc[ai][bj][m][n], 0, 0, 0); __builtin_amdgcn_s_setprio(0); } while (0)
; #define PG8_WAIT_V(n) asm volatile("s_waitcnt vmcnt(" #n ")" ::: "memory")
; #define PG8_WAIT_L(n) asm volatile("s_waitcnt lgkmcnt(" #n ")" ::: "memory")
; template <class Epi, class Sched>
; __device__ __forceinline__ void gemm_phase(LAS unsigned char* lds, const Gemm g, const Sched& S, const Epi& E) {
;     ...
;             PG8_BAR; PG8_WAIT_L(0); PG8_MMA(1, 0, At, B0); PG8_BAR; PG8_SCHED;
;             PG8_STAGE(PG8_SB(1, 1), b3 + hstep, voffB);
;             PG8_WAIT_V(6); PG8_BAR; PG8_MMA(1, 1, At, B1); PG8_BAR;
;         }
;         E(acc, cur, wr, wc, fr, fq);
;         if (!has_next) break;
;     __device__ __forceinline__ void operator()(const AccT& acc, const Unit& u, int wr, int wc, int fr, int fq) const {
;     ...
;         const int row0 = u.pm * 256 + wr * 64 + fr, hc0 = u.pn * 128 + wc * 32 + 8 * fq;
; #pragma unroll
;         for (int ai = 0; ai < 2; ++ai)
; #pragma unroll
;             for (int m = 0; m < 4; ++m) {
;                 const f32x4 a0 = acc[ai][0][m][0], a1 = acc[ai][0][m][1], b0 = acc[ai][1][m][0], b1 = acc[ai][1][m][1];
;                 u32x4 w;
;                 w.x = cvt_pk_bf16(silu_f(a0[0]) * b0[0], silu_f(a0[1]) * b0[1]); w.y = cvt_pk_bf16(silu_f(a0[2]) * b0[2], silu_f(a0[3]) * b0[3]);
;                 w.z = cvt_pk_bf16(silu_f(a1[0]) * b1[0], silu_f(a1[1]) * b1[1]); w.w = cvt_pk_bf16(silu_f(a1[2]) * b1[2], silu_f(a1[3]) * b1[3]);
;                 *(u32x4*)(H + (size_t)(row0 + ai * 128 + m * 16) * DFF + hc0) = w;
;             }
	s_waitcnt lgkmcnt(0)
	v_mfma_f32_16x16x32_bf16 v[60:63], v[150:153], v[166:169], v[60:63]
	v_mfma_f32_16x16x32_bf16 v[56:59], v[158:161], v[166:169], v[56:59]
	v_mfma_f32_16x16x32_bf16 v[44:47], v[150:153], v[174:177], v[44:47]
	v_mfma_f32_16x16x32_bf16 v[40:43], v[158:161], v[174:177], v[40:43]
	v_mfma_f32_16x16x32_bf16 v[28:31], v[150:153], v[182:185], v[28:31]
	v_mfma_f32_16x16x32_bf16 v[24:27], v[158:161], v[182:185], v[24:27]
	v_mfma_f32_16x16x32_bf16 v[12:15], v[150:153], v[190:193], v[12:15]
	v_mfma_f32_16x16x32_bf16 v[8:11], v[158:161], v[190:193], v[8:11]
	v_mfma_f32_16x16x32_bf16 v[60:63], v[154:157], v[170:173], v[60:63]
	v_mfma_f32_16x16x32_bf16 v[56:59], v[162:165], v[170:173], v[56:59]
	v_mfma_f32_16x16x32_bf16 v[44:47], v[154:157], v[178:181], v[44:47]
	v_mfma_f32_16x16x32_bf16 v[40:43], v[162:165], v[178:181], v[40:43]
	v_mfma_f32_16x16x32_bf16 v[28:31], v[154:157], v[186:189], v[28:31]
	v_mfma_f32_16x16x32_bf16 v[24:27], v[162:165], v[186:189], v[24:27]
	v_mfma_f32_16x16x32_bf16 v[12:15], v[154:157], v[194:197], v[12:15]
	v_mfma_f32_16x16x32_bf16 v[8:11], v[162:165], v[194:197], v[8:11]
	s_barrier
	s_setprio 0
	s_add_u32 s18, s18, 0x40080
	s_addc_u32 s19, s19, 0
	s_add_i32 s20, s20, s25
	s_mov_b32 m0, s20
	s_nop 0
	global_load_lds_dwordx4 v132, s[18:19]
	s_add_i32 m0, s20, 0x2000
	s_nop 0
	global_load_lds_dwordx4 v128, s[18:19]
	s_waitcnt vmcnt(8)
	s_setprio 1
	s_barrier
	v_mfma_f32_16x16x32_bf16 v[52:55], v[202:205], v[166:169], v[52:55]
	v_mfma_f32_16x16x32_bf16 v[48:51], v[210:213], v[166:169], v[48:51]
	v_mfma_f32_16x16x32_bf16 v[36:39], v[202:205], v[174:177], v[36:39]
	v_mfma_f32_16x16x32_bf16 v[32:35], v[210:213], v[174:177], v[32:35]
	v_mfma_f32_16x16x32_bf16 v[20:23], v[202:205], v[182:185], v[20:23]
	v_mfma_f32_16x16x32_bf16 v[16:19], v[210:213], v[182:185], v[16:19]
	v_mfma_f32_16x16x32_bf16 v[4:7], v[202:205], v[190:193], v[4:7]
	v_mfma_f32_16x16x32_bf16 v[0:3], v[210:213], v[190:193], v[0:3]
	v_mfma_f32_16x16x32_bf16 v[52:55], v[206:209], v[170:173], v[52:55]
	v_mfma_f32_16x16x32_bf16 v[48:51], v[214:217], v[170:173], v[48:51]
	v_mfma_f32_16x16x32_bf16 v[36:39], v[206:209], v[178:181], v[36:39]
	v_mfma_f32_16x16x32_bf16 v[32:35], v[214:217], v[178:181], v[32:35]
	v_mfma_f32_16x16x32_bf16 v[20:23], v[206:209], v[186:189], v[20:23]
	v_mfma_f32_16x16x32_bf16 v[16:19], v[214:217], v[186:189], v[16:19]
	v_mfma_f32_16x16x32_bf16 v[4:7], v[206:209], v[194:197], v[4:7]
	v_mfma_f32_16x16x32_bf16 v[0:3], v[214:217], v[194:197], v[0:3]
	s_add_i32 s46, s46, 2
	s_cmp_gt_u32 s46, 13
	s_cbranch_scc1 .Lconc_last_g11
	s_barrier
	s_setprio 0
	s_add_u32 s16, s16, 0x100
	s_addc_u32 s17, s17, 0
	s_add_u32 s44, s44, 0x100
	s_addc_u32 s45, s45, 0
	s_branch .LBB0_1021
.Lconc_last_g11:
	v_readfirstlane_b32 s5, v200
	s_nop 3
	s_cmp_gt_u32 s5, 0xff
	s_cbranch_scc1 .Lconc_epi1_g11
	s_barrier
	s_setprio 0
	v_mul_f32_e32 v152, 0xbfb8aa3b, v124
	v_mov_b32_e32 v150, v144
	v_mov_b32_e32 v151, v145
	s_lshl_b32 s5, s14, 8
	v_exp_f32_e32 v153, v152
	v_mul_f32_e32 v152, 0xbfb8aa3b, v125
	s_add_i32 s5, s5, s33
	v_exp_f32_e32 v154, v152
	v_add_u32_e32 v150, s5, v150
	s_lshl_b32 s5, s41, 7
	s_or_b32 s5, s5, s34
	v_lshl_add_u32 v152, v151, 3, s5
	v_add_f32_e32 v151, 1.0, v153
	v_rcp_f32_e32 v151, v151
	v_add_f32_e32 v153, 1.0, v154
	v_rcp_f32_e32 v154, v153
	v_ashrrev_i32_e32 v153, 31, v152
	v_mul_f32_e32 v124, v124, v151
	v_mul_f32_e32 v120, v124, v120
	v_mul_f32_e32 v124, v125, v154
	v_mul_f32_e32 v125, 0xbfb8aa3b, v126
	v_exp_f32_e32 v125, v125
	v_mul_f32_e32 v151, 0xbfb8aa3b, v127
	v_exp_f32_e32 v151, v151
	v_mul_f32_e32 v121, v124, v121
	v_add_f32_e32 v124, 1.0, v125
	v_rcp_f32_e32 v124, v124
	v_add_f32_e32 v125, 1.0, v151
	v_rcp_f32_e32 v125, v125
	v_cvt_pk_bf16_f32 v120, v120, v121
	v_mul_f32_e32 v121, v126, v124
	v_mul_f32_e32 v124, 0xbfb8aa3b, v116
	v_mul_f32_e32 v121, v121, v122
	v_mul_f32_e32 v122, v127, v125
	v_exp_f32_e32 v124, v124
	v_mul_f32_e32 v125, 0xbfb8aa3b, v117
	v_exp_f32_e32 v125, v125
	v_mul_f32_e32 v122, v122, v123
	v_add_f32_e32 v123, 1.0, v124
	v_rcp_f32_e32 v123, v123
	v_add_f32_e32 v124, 1.0, v125
	v_rcp_f32_e32 v124, v124
	v_cvt_pk_bf16_f32 v121, v121, v122
	v_mul_f32_e32 v116, v116, v123
	v_mul_f32_e32 v112, v116, v112
	v_mul_f32_e32 v116, v117, v124
	v_mul_f32_e32 v117, 0xbfb8aa3b, v118
	v_exp_f32_e32 v117, v117
	v_mul_f32_e32 v122, 0xbfb8aa3b, v119
	v_exp_f32_e32 v122, v122
	v_mul_f32_e32 v113, v116, v113
	v_add_f32_e32 v116, 1.0, v117
	v_rcp_f32_e32 v116, v116
	v_add_f32_e32 v117, 1.0, v122
	v_rcp_f32_e32 v117, v117
	v_cvt_pk_bf16_f32 v122, v112, v113
	v_mul_f32_e32 v112, v118, v116
	v_mul_f32_e32 v118, 0xbfb8aa3b, v108
	v_mul_f32_e32 v113, v119, v117
	v_exp_f32_e32 v118, v118
	v_mul_f32_e32 v119, 0xbfb8aa3b, v109
	v_exp_f32_e32 v119, v119
	v_mul_f32_e32 v112, v112, v114
	v_add_f32_e32 v118, 1.0, v118
	v_rcp_f32_e32 v118, v118
	v_add_f32_e32 v119, 1.0, v119
	v_rcp_f32_e32 v119, v119
	v_mul_f32_e32 v113, v113, v115
	v_cvt_pk_bf16_f32 v123, v112, v113
	v_mov_b64_e32 v[112:113], s[82:83]
	v_mad_i64_i32 v[116:117], s[16:17], v150, s40, v[112:113]
	v_lshlrev_b64 v[114:115], 1, v[152:153]
	v_mul_f32_e32 v108, v108, v118
	v_lshl_add_u64 v[116:117], v[116:117], 0, v[114:115]
	v_mul_f32_e32 v104, v108, v104
	v_mul_f32_e32 v108, v109, v119
	v_mul_f32_e32 v109, 0xbfb8aa3b, v110
	global_store_dwordx4 v[116:117], v[120:123], off
	v_exp_f32_e32 v109, v109
	v_mul_f32_e32 v116, 0xbfb8aa3b, v111
	v_exp_f32_e32 v116, v116
	v_mul_f32_e32 v105, v108, v105
	v_add_f32_e32 v108, 1.0, v109
	v_rcp_f32_e32 v108, v108
	v_add_f32_e32 v109, 1.0, v116
	v_rcp_f32_e32 v109, v109
	v_cvt_pk_bf16_f32 v104, v104, v105
	v_mul_f32_e32 v105, v110, v108
; __device__ __forceinline__ unsigned cvt_pk_bf16(float lo, float hi) { unsigned r; asm volatile("v_cvt_pk_bf16_f32 %0, %1, %2" : "=v"(r) : "v"(lo), "v"(hi)); return r; }
; __device__ __forceinline__ float silu_f(float a) { return a * __builtin_amdgcn_rcpf(1.0f + __expf(-a)); }
;     __device__ __forceinline__ void operator()(const AccT& acc, const Unit& u, int wr, int wc, int fr, int fq) const {
;     ...
;         for (int ai = 0; ai < 2; ++ai)
; #pragma unroll
;             for (int m = 0; m < 4; ++m) {
;                 const f32x4 a0 = acc[ai][0][m][0], a1 = acc[ai][0][m][1], b0 = acc[ai][1][m][0], b1 = acc[ai][1][m][1];
;                 u32x4 w;
;                 w.x = cvt_pk_bf16(silu_f(a0[0]) * b0[0], silu_f(a0[1]) * b0[1]); w.y = cvt_pk_bf16(silu_f(a0[2]) * b0[2], silu_f(a0[3]) * b0[3]);
;                 w.z = cvt_pk_bf16(silu_f(a1[0]) * b1[0], silu_f(a1[1]) * b1[1]); w.w = cvt_pk_bf16(silu_f(a1[2]) * b1[2], silu_f(a1[3]) * b1[3]);
;                 *(u32x4*)(H + (size_t)(row0 + ai * 128 + m * 16) * DFF + hc0) = w;
;             }
	v_mul_f32_e32 v108, 0xbfb8aa3b, v100
	v_mul_f32_e32 v105, v105, v106
	v_mul_f32_e32 v106, v111, v109
	v_exp_f32_e32 v108, v108
	v_mul_f32_e32 v109, 0xbfb8aa3b, v101
	v_exp_f32_e32 v109, v109
	v_mul_f32_e32 v106, v106, v107
	v_add_f32_e32 v107, 1.0, v108
	v_rcp_f32_e32 v107, v107
	v_add_f32_e32 v108, 1.0, v109
	v_rcp_f32_e32 v108, v108
	v_cvt_pk_bf16_f32 v105, v105, v106
	v_mul_f32_e32 v100, v100, v107
	v_mul_f32_e32 v96, v100, v96
	v_mul_f32_e32 v100, v101, v108
	v_mul_f32_e32 v101, 0xbfb8aa3b, v102
	v_exp_f32_e32 v101, v101
	v_mul_f32_e32 v106, 0xbfb8aa3b, v103
	v_exp_f32_e32 v106, v106
	v_mul_f32_e32 v97, v100, v97
	v_add_f32_e32 v100, 1.0, v101
	v_rcp_f32_e32 v100, v100
	v_add_f32_e32 v101, 1.0, v106
	v_rcp_f32_e32 v101, v101
	v_cvt_pk_bf16_f32 v106, v96, v97
	v_mul_f32_e32 v96, v102, v100
	v_mul_f32_e32 v96, v96, v98
	v_mul_f32_e32 v97, v103, v101
	v_mul_f32_e32 v98, 0xbfb8aa3b, v92
	v_mul_f32_e32 v97, v97, v99
	v_exp_f32_e32 v98, v98
	v_mul_f32_e32 v99, 0xbfb8aa3b, v93
	v_exp_f32_e32 v99, v99
	v_cvt_pk_bf16_f32 v107, v96, v97
	v_add_f32_e32 v98, 1.0, v98
	v_rcp_f32_e32 v98, v98
	v_add_f32_e32 v99, 1.0, v99
	v_rcp_f32_e32 v99, v99
	v_add_u32_e32 v96, 16, v150
	v_mad_i64_i32 v[96:97], s[16:17], v96, s40, v[112:113]
	v_mul_f32_e32 v92, v92, v98
	v_lshl_add_u64 v[96:97], v[96:97], 0, v[114:115]
	v_mul_f32_e32 v88, v92, v88
	v_mul_f32_e32 v92, v93, v99
	v_mul_f32_e32 v93, 0xbfb8aa3b, v94
	global_store_dwordx4 v[96:97], v[104:107], off
	v_exp_f32_e32 v93, v93
	v_mul_f32_e32 v96, 0xbfb8aa3b, v95
	v_exp_f32_e32 v96, v96
	v_mul_f32_e32 v89, v92, v89
	v_add_f32_e32 v92, 1.0, v93
	v_rcp_f32_e32 v92, v92
	v_add_f32_e32 v93, 1.0, v96
	v_rcp_f32_e32 v93, v93
	v_cvt_pk_bf16_f32 v88, v88, v89
	v_mul_f32_e32 v89, v94, v92
	v_mul_f32_e32 v92, 0xbfb8aa3b, v84
	v_mul_f32_e32 v89, v89, v90
	v_mul_f32_e32 v90, v95, v93
	v_exp_f32_e32 v92, v92
	v_mul_f32_e32 v93, 0xbfb8aa3b, v85
	v_exp_f32_e32 v93, v93
	v_mul_f32_e32 v90, v90, v91
	v_add_f32_e32 v91, 1.0, v92
	v_rcp_f32_e32 v91, v91
	v_add_f32_e32 v92, 1.0, v93
	v_rcp_f32_e32 v92, v92
	v_cvt_pk_bf16_f32 v89, v89, v90
	v_mul_f32_e32 v84, v84, v91
	v_mul_f32_e32 v80, v84, v80
	v_mul_f32_e32 v84, v85, v92
	v_mul_f32_e32 v85, 0xbfb8aa3b, v86
	v_exp_f32_e32 v85, v85
	v_mul_f32_e32 v90, 0xbfb8aa3b, v87
	v_exp_f32_e32 v90, v90
	v_mul_f32_e32 v81, v84, v81
	v_add_f32_e32 v84, 1.0, v85
	v_rcp_f32_e32 v84, v84
	v_add_f32_e32 v85, 1.0, v90
	v_rcp_f32_e32 v85, v85
	v_cvt_pk_bf16_f32 v90, v80, v81
	v_mul_f32_e32 v80, v86, v84
	v_mul_f32_e32 v80, v80, v82
	v_mul_f32_e32 v81, v87, v85
	v_mul_f32_e32 v82, 0xbfb8aa3b, v76
	v_mul_f32_e32 v81, v81, v83
	v_exp_f32_e32 v82, v82
	v_mul_f32_e32 v83, 0xbfb8aa3b, v77
	v_exp_f32_e32 v83, v83
	v_cvt_pk_bf16_f32 v91, v80, v81
	v_add_f32_e32 v82, 1.0, v82
	v_rcp_f32_e32 v82, v82
	v_add_f32_e32 v83, 1.0, v83
	v_rcp_f32_e32 v83, v83
	v_add_u32_e32 v80, 32, v150
	v_mad_i64_i32 v[80:81], s[16:17], v80, s40, v[112:113]
	v_mul_f32_e32 v76, v76, v82
	v_lshl_add_u64 v[80:81], v[80:81], 0, v[114:115]
	v_mul_f32_e32 v72, v76, v72
	v_mul_f32_e32 v76, v77, v83
	v_mul_f32_e32 v77, 0xbfb8aa3b, v78
	global_store_dwordx4 v[80:81], v[88:91], off
	v_exp_f32_e32 v77, v77
	v_mul_f32_e32 v80, 0xbfb8aa3b, v79
	v_exp_f32_e32 v80, v80
	v_mul_f32_e32 v73, v76, v73
	v_add_f32_e32 v76, 1.0, v77
	v_rcp_f32_e32 v76, v76
	v_add_f32_e32 v77, 1.0, v80
	v_rcp_f32_e32 v77, v77
	v_cvt_pk_bf16_f32 v72, v72, v73
	v_mul_f32_e32 v73, v78, v76
	v_mul_f32_e32 v76, 0xbfb8aa3b, v68
	v_mul_f32_e32 v73, v73, v74
	v_mul_f32_e32 v74, v79, v77
	v_exp_f32_e32 v76, v76
	v_mul_f32_e32 v77, 0xbfb8aa3b, v69
	v_exp_f32_e32 v77, v77
	v_mul_f32_e32 v74, v74, v75
	v_add_f32_e32 v75, 1.0, v76
	v_rcp_f32_e32 v75, v75
	v_add_f32_e32 v76, 1.0, v77
	v_rcp_f32_e32 v76, v76
	v_cvt_pk_bf16_f32 v73, v73, v74
	v_mul_f32_e32 v68, v68, v75
	v_mul_f32_e32 v64, v68, v64
	v_mul_f32_e32 v68, v69, v76
	v_mul_f32_e32 v69, 0xbfb8aa3b, v70
	v_exp_f32_e32 v69, v69
	v_mul_f32_e32 v74, 0xbfb8aa3b, v71
	v_exp_f32_e32 v74, v74
	v_mul_f32_e32 v65, v68, v65
	v_add_f32_e32 v68, 1.0, v69
	v_rcp_f32_e32 v68, v68
	v_add_f32_e32 v69, 1.0, v74
	v_rcp_f32_e32 v69, v69
	v_cvt_pk_bf16_f32 v74, v64, v65
	v_mul_f32_e32 v64, v70, v68
	v_mul_f32_e32 v64, v64, v66
	v_mul_f32_e32 v65, v71, v69
	v_mul_f32_e32 v66, 0xbfb8aa3b, v60
	v_mul_f32_e32 v65, v65, v67
	v_exp_f32_e32 v66, v66
	v_mul_f32_e32 v67, 0xbfb8aa3b, v61
	v_cvt_pk_bf16_f32 v75, v64, v65
	v_add_u32_e32 v64, 48, v150
	v_exp_f32_e32 v67, v67
	v_mad_i64_i32 v[64:65], s[16:17], v64, s40, v[112:113]
	v_lshl_add_u64 v[64:65], v[64:65], 0, v[114:115]
	global_store_dwordx4 v[64:65], v[72:75], off
	v_add_f32_e32 v64, 1.0, v66
	v_rcp_f32_e32 v64, v64
	v_add_f32_e32 v65, 1.0, v67
	v_rcp_f32_e32 v65, v65
	v_add_u32_e32 v66, 0x80, v150
	v_mul_f32_e32 v60, v60, v64
	v_mul_f32_e32 v52, v60, v52
	v_mul_f32_e32 v60, v61, v65
	v_mul_f32_e32 v61, 0xbfb8aa3b, v62
	v_exp_f32_e32 v61, v61
	v_mul_f32_e32 v64, 0xbfb8aa3b, v63
	v_exp_f32_e32 v64, v64
	v_mul_f32_e32 v53, v60, v53
	v_add_f32_e32 v60, 1.0, v61
	v_rcp_f32_e32 v60, v60
	v_add_f32_e32 v61, 1.0, v64
	v_rcp_f32_e32 v61, v61
	v_cvt_pk_bf16_f32 v52, v52, v53
	v_mul_f32_e32 v53, v62, v60
	v_mul_f32_e32 v60, 0xbfb8aa3b, v56
	v_exp_f32_e32 v60, v60
	v_mul_f32_e32 v53, v53, v54
	v_mul_f32_e32 v54, v63, v61
	v_mul_f32_e32 v61, 0xbfb8aa3b, v57
	v_exp_f32_e32 v61, v61
	v_mul_f32_e32 v54, v54, v55
	v_add_f32_e32 v55, 1.0, v60
	v_rcp_f32_e32 v55, v55
	v_add_f32_e32 v60, 1.0, v61
	v_rcp_f32_e32 v60, v60
	v_cvt_pk_bf16_f32 v53, v53, v54
	v_mul_f32_e32 v54, v56, v55
	v_mul_f32_e32 v55, 0xbfb8aa3b, v58
	v_exp_f32_e32 v55, v55
	v_mul_f32_e32 v56, 0xbfb8aa3b, v59
	v_exp_f32_e32 v56, v56
; __device__ __forceinline__ unsigned cvt_pk_bf16(float lo, float hi) { unsigned r; asm volatile("v_cvt_pk_bf16_f32 %0, %1, %2" : "=v"(r) : "v"(lo), "v"(hi)); return r; }
; __device__ __forceinline__ float silu_f(float a) { return a * __builtin_amdgcn_rcpf(1.0f + __expf(-a)); }
; template <class Epi, class Sched>
; __device__ __forceinline__ void gemm_phase(LAS unsigned char* lds, const Gemm g, const Sched& S, const Epi& E) {
;     ...
;         E(acc, cur, wr, wc, fr, fq);
;         if (!has_next) break;
; #pragma unroll
;         for (int a = 0; a < 2; ++a)
; #pragma unroll
;             for (int b = 0; b < 2; ++b)
; #pragma unroll
;                 for (int m = 0; m < 4; ++m)
; #pragma unroll
;                     for (int n = 0; n < 2; ++n) acc[a][b][m][n] = (f32x4){0.f, 0.f, 0.f, 0.f};
;         cur = nxt; cA = nA; cB = nB; ++ui;
;     __device__ __forceinline__ void operator()(const AccT& acc, const Unit& u, int wr, int wc, int fr, int fq) const {
;     ...
;         for (int ai = 0; ai < 2; ++ai)
; #pragma unroll
;             for (int m = 0; m < 4; ++m) {
;                 const f32x4 a0 = acc[ai][0][m][0], a1 = acc[ai][0][m][1], b0 = acc[ai][1][m][0], b1 = acc[ai][1][m][1];
;                 u32x4 w;
;                 w.x = cvt_pk_bf16(silu_f(a0[0]) * b0[0], silu_f(a0[1]) * b0[1]); w.y = cvt_pk_bf16(silu_f(a0[2]) * b0[2], silu_f(a0[3]) * b0[3]);
;                 w.z = cvt_pk_bf16(silu_f(a1[0]) * b1[0], silu_f(a1[1]) * b1[1]); w.w = cvt_pk_bf16(silu_f(a1[2]) * b1[2], silu_f(a1[3]) * b1[3]);
;                 *(u32x4*)(H + (size_t)(row0 + ai * 128 + m * 16) * DFF + hc0) = w;
;             }
	v_mul_f32_e32 v48, v54, v48
	v_mul_f32_e32 v54, v57, v60
	v_mul_f32_e32 v49, v54, v49
	v_add_f32_e32 v54, 1.0, v55
	v_rcp_f32_e32 v55, v54
	v_add_f32_e32 v54, 1.0, v56
	v_rcp_f32_e32 v56, v54
	v_cvt_pk_bf16_f32 v54, v48, v49
	v_mul_f32_e32 v48, v58, v55
	v_mul_f32_e32 v48, v48, v50
	v_mul_f32_e32 v49, v59, v56
	v_mul_f32_e32 v50, 0xbfb8aa3b, v44
	v_mul_f32_e32 v49, v49, v51
	v_exp_f32_e32 v50, v50
	v_mul_f32_e32 v51, 0xbfb8aa3b, v45
	v_exp_f32_e32 v51, v51
	v_cvt_pk_bf16_f32 v55, v48, v49
	v_add_f32_e32 v50, 1.0, v50
	v_rcp_f32_e32 v50, v50
	v_add_f32_e32 v51, 1.0, v51
	v_rcp_f32_e32 v51, v51
	v_mad_i64_i32 v[48:49], s[16:17], v66, s40, v[112:113]
	v_mul_f32_e32 v44, v44, v50
	v_mul_f32_e32 v36, v44, v36
	v_mul_f32_e32 v44, v45, v51
	v_mul_f32_e32 v45, 0xbfb8aa3b, v46
	v_exp_f32_e32 v45, v45
	v_lshl_add_u64 v[48:49], v[48:49], 0, v[114:115]
	global_store_dwordx4 v[48:49], v[52:55], off
	v_mul_f32_e32 v48, 0xbfb8aa3b, v47
	v_exp_f32_e32 v48, v48
	v_mul_f32_e32 v37, v44, v37
	v_add_f32_e32 v44, 1.0, v45
	v_rcp_f32_e32 v44, v44
	v_add_f32_e32 v45, 1.0, v48
	v_rcp_f32_e32 v45, v45
	v_cvt_pk_bf16_f32 v36, v36, v37
	v_mul_f32_e32 v37, v46, v44
	v_mul_f32_e32 v44, 0xbfb8aa3b, v40
	v_exp_f32_e32 v44, v44
	v_mul_f32_e32 v37, v37, v38
	v_mul_f32_e32 v38, v47, v45
	v_mul_f32_e32 v45, 0xbfb8aa3b, v41
	v_exp_f32_e32 v45, v45
	v_mul_f32_e32 v38, v38, v39
	v_add_f32_e32 v39, 1.0, v44
	v_rcp_f32_e32 v39, v39
	v_add_f32_e32 v44, 1.0, v45
	v_rcp_f32_e32 v44, v44
	v_cvt_pk_bf16_f32 v37, v37, v38
	v_mul_f32_e32 v38, v40, v39
	v_mul_f32_e32 v39, 0xbfb8aa3b, v42
	v_exp_f32_e32 v39, v39
	v_mul_f32_e32 v40, 0xbfb8aa3b, v43
	v_exp_f32_e32 v40, v40
	v_mul_f32_e32 v32, v38, v32
	v_mul_f32_e32 v38, v41, v44
	v_mul_f32_e32 v33, v38, v33
	v_add_f32_e32 v38, 1.0, v39
	v_rcp_f32_e32 v39, v38
	v_add_f32_e32 v38, 1.0, v40
	v_rcp_f32_e32 v40, v38
	v_cvt_pk_bf16_f32 v38, v32, v33
	v_mul_f32_e32 v32, v42, v39
	v_mul_f32_e32 v32, v32, v34
	v_mul_f32_e32 v33, v43, v40
	v_mul_f32_e32 v34, 0xbfb8aa3b, v28
	v_mul_f32_e32 v33, v33, v35
	v_exp_f32_e32 v34, v34
	v_mul_f32_e32 v35, 0xbfb8aa3b, v29
	v_exp_f32_e32 v35, v35
	v_cvt_pk_bf16_f32 v39, v32, v33
	v_add_f32_e32 v34, 1.0, v34
	v_rcp_f32_e32 v34, v34
	v_add_f32_e32 v35, 1.0, v35
	v_rcp_f32_e32 v35, v35
	v_add_u32_e32 v32, 0x90, v150
	v_mul_f32_e32 v28, v28, v34
	v_mul_f32_e32 v20, v28, v20
	v_mul_f32_e32 v28, v29, v35
	v_mul_f32_e32 v29, 0xbfb8aa3b, v30
	v_exp_f32_e32 v29, v29
	v_mad_i64_i32 v[32:33], s[16:17], v32, s40, v[112:113]
	v_lshl_add_u64 v[32:33], v[32:33], 0, v[114:115]
	global_store_dwordx4 v[32:33], v[36:39], off
	v_mul_f32_e32 v32, 0xbfb8aa3b, v31
	v_exp_f32_e32 v32, v32
	v_mul_f32_e32 v21, v28, v21
	v_add_f32_e32 v28, 1.0, v29
	v_rcp_f32_e32 v28, v28
	v_add_f32_e32 v29, 1.0, v32
	v_rcp_f32_e32 v29, v29
	v_cvt_pk_bf16_f32 v20, v20, v21
	v_mul_f32_e32 v21, v30, v28
	v_mul_f32_e32 v28, 0xbfb8aa3b, v24
	v_exp_f32_e32 v28, v28
	v_mul_f32_e32 v21, v21, v22
	v_mul_f32_e32 v22, v31, v29
	v_mul_f32_e32 v29, 0xbfb8aa3b, v25
	v_exp_f32_e32 v29, v29
	v_mul_f32_e32 v22, v22, v23
	v_add_f32_e32 v23, 1.0, v28
	v_rcp_f32_e32 v23, v23
	v_add_f32_e32 v28, 1.0, v29
	v_rcp_f32_e32 v28, v28
	v_cvt_pk_bf16_f32 v21, v21, v22
	v_mul_f32_e32 v22, v24, v23
	v_mul_f32_e32 v23, 0xbfb8aa3b, v26
	v_exp_f32_e32 v23, v23
	v_mul_f32_e32 v24, 0xbfb8aa3b, v27
	v_exp_f32_e32 v24, v24
	v_mul_f32_e32 v16, v22, v16
	v_mul_f32_e32 v22, v25, v28
	v_mul_f32_e32 v17, v22, v17
	v_add_f32_e32 v22, 1.0, v23
	v_rcp_f32_e32 v23, v22
	v_add_f32_e32 v22, 1.0, v24
	v_rcp_f32_e32 v24, v22
	v_cvt_pk_bf16_f32 v22, v16, v17
	v_mul_f32_e32 v16, v26, v23
	v_mul_f32_e32 v16, v16, v18
	v_mul_f32_e32 v17, v27, v24
	v_mul_f32_e32 v18, 0xbfb8aa3b, v12
	v_mul_f32_e32 v17, v17, v19
	v_exp_f32_e32 v18, v18
	v_mul_f32_e32 v19, 0xbfb8aa3b, v13
	v_exp_f32_e32 v19, v19
	v_cvt_pk_bf16_f32 v23, v16, v17
	v_add_f32_e32 v18, 1.0, v18
	v_rcp_f32_e32 v18, v18
	v_add_f32_e32 v19, 1.0, v19
	v_rcp_f32_e32 v19, v19
	v_add_u32_e32 v16, 0xa0, v150
	v_mul_f32_e32 v12, v12, v18
	v_mul_f32_e32 v4, v12, v4
	v_mul_f32_e32 v12, v13, v19
	v_mul_f32_e32 v13, 0xbfb8aa3b, v14
	v_exp_f32_e32 v13, v13
	v_mad_i64_i32 v[16:17], s[16:17], v16, s40, v[112:113]
	v_lshl_add_u64 v[16:17], v[16:17], 0, v[114:115]
	global_store_dwordx4 v[16:17], v[20:23], off
	v_mul_f32_e32 v16, 0xbfb8aa3b, v15
	v_exp_f32_e32 v16, v16
	v_mul_f32_e32 v5, v12, v5
	v_add_f32_e32 v12, 1.0, v13
	v_rcp_f32_e32 v12, v12
	v_add_f32_e32 v13, 1.0, v16
	v_rcp_f32_e32 v13, v13
	v_cvt_pk_bf16_f32 v4, v4, v5
	v_mul_f32_e32 v5, v14, v12
	v_mul_f32_e32 v12, 0xbfb8aa3b, v8
	v_exp_f32_e32 v12, v12
	v_mul_f32_e32 v5, v5, v6
	v_mul_f32_e32 v6, v15, v13
	v_mul_f32_e32 v13, 0xbfb8aa3b, v9
	v_exp_f32_e32 v13, v13
	v_mul_f32_e32 v6, v6, v7
	v_add_f32_e32 v7, 1.0, v12
	v_rcp_f32_e32 v7, v7
	v_add_f32_e32 v12, 1.0, v13
	v_rcp_f32_e32 v12, v12
	v_cvt_pk_bf16_f32 v5, v5, v6
	v_mul_f32_e32 v6, v8, v7
	v_mul_f32_e32 v7, 0xbfb8aa3b, v10
	v_exp_f32_e32 v7, v7
	v_mul_f32_e32 v8, 0xbfb8aa3b, v11
	v_exp_f32_e32 v8, v8
	v_mul_f32_e32 v0, v6, v0
	v_mul_f32_e32 v6, v9, v12
	v_mul_f32_e32 v1, v6, v1
	v_add_f32_e32 v6, 1.0, v7
	v_rcp_f32_e32 v7, v6
	v_add_f32_e32 v6, 1.0, v8
	v_rcp_f32_e32 v8, v6
	v_cvt_pk_bf16_f32 v6, v0, v1
	v_mul_f32_e32 v0, v10, v7
	v_mul_f32_e32 v0, v0, v2
	v_mul_f32_e32 v1, v11, v8
	v_mul_f32_e32 v1, v1, v3
	v_cvt_pk_bf16_f32 v7, v0, v1
	v_add_u32_e32 v0, 0xb0, v150
	v_mad_i64_i32 v[0:1], s[16:17], v0, s40, v[112:113]
	v_lshl_add_u64 v[0:1], v[0:1], 0, v[114:115]
	s_and_b64 vcc, exec, s[2:3]
	s_mov_b32 s41, s4
	s_mov_b32 s14, s6
	s_mov_b64 s[18:19], s[12:13]
	s_mov_b64 s[16:17], s[10:11]
	global_store_dwordx4 v[0:1], v[4:7], off
	s_cbranch_vccz .LBB0_1018
	s_branch .Lconc_end_g11
; __device__ __forceinline__ unsigned cvt_pk_bf16(float lo, float hi) { unsigned r; asm volatile("v_cvt_pk_bf16_f32 %0, %1, %2" : "=v"(r) : "v"(lo), "v"(hi)); return r; }
; __device__ __forceinline__ float silu_f(float a) { return a * __builtin_amdgcn_rcpf(1.0f + __expf(-a)); }
;     __device__ __forceinline__ void operator()(const AccT& acc, const Unit& u, int wr, int wc, int fr, int fq) const {
;         asm volatile("" : "+v"(fr), "+v"(fq));
;         const int row0 = u.pm * 256 + wr * 64 + fr, hc0 = u.pn * 128 + wc * 32 + 8 * fq;
; #pragma unroll
;         for (int ai = 0; ai < 2; ++ai)
; #pragma unroll
;             for (int m = 0; m < 4; ++m) {
;                 const f32x4 a0 = acc[ai][0][m][0], a1 = acc[ai][0][m][1], b0 = acc[ai][1][m][0], b1 = acc[ai][1][m][1];
;                 u32x4 w;
;                 w.x = cvt_pk_bf16(silu_f(a0[0]) * b0[0], silu_f(a0[1]) * b0[1]); w.y = cvt_pk_bf16(silu_f(a0[2]) * b0[2], silu_f(a0[3]) * b0[3]);
;                 w.z = cvt_pk_bf16(silu_f(a1[0]) * b1[0], silu_f(a1[1]) * b1[1]); w.w = cvt_pk_bf16(silu_f(a1[2]) * b1[2], silu_f(a1[3]) * b1[3]);
;                 *(u32x4*)(H + (size_t)(row0 + ai * 128 + m * 16) * DFF + hc0) = w;
.Lconc_epi1_g11:
	s_setprio 0
	v_mul_f32_e32 v152, 0xbfb8aa3b, v124
	v_mov_b32_e32 v150, v144
	v_mov_b32_e32 v151, v145
	s_lshl_b32 s5, s14, 8
	v_exp_f32_e32 v153, v152
	v_mul_f32_e32 v152, 0xbfb8aa3b, v125
	s_add_i32 s5, s5, s33
	v_exp_f32_e32 v154, v152
	v_add_u32_e32 v150, s5, v150
	s_lshl_b32 s5, s41, 7
	s_or_b32 s5, s5, s34
	v_lshl_add_u32 v152, v151, 3, s5
	v_add_f32_e32 v151, 1.0, v153
	v_rcp_f32_e32 v151, v151
	v_add_f32_e32 v153, 1.0, v154
	v_rcp_f32_e32 v154, v153
	v_ashrrev_i32_e32 v153, 31, v152
	v_mul_f32_e32 v124, v124, v151
	v_mul_f32_e32 v120, v124, v120
	v_mul_f32_e32 v124, v125, v154
	v_mul_f32_e32 v125, 0xbfb8aa3b, v126
	v_exp_f32_e32 v125, v125
	v_mul_f32_e32 v151, 0xbfb8aa3b, v127
	v_exp_f32_e32 v151, v151
	v_mul_f32_e32 v121, v124, v121
	v_add_f32_e32 v124, 1.0, v125
	v_rcp_f32_e32 v124, v124
	v_add_f32_e32 v125, 1.0, v151
	v_rcp_f32_e32 v125, v125
	v_cvt_pk_bf16_f32 v120, v120, v121
	v_mul_f32_e32 v121, v126, v124
	v_mul_f32_e32 v124, 0xbfb8aa3b, v116
	v_mul_f32_e32 v121, v121, v122
	v_mul_f32_e32 v122, v127, v125
	v_exp_f32_e32 v124, v124
	v_mul_f32_e32 v125, 0xbfb8aa3b, v117
	v_exp_f32_e32 v125, v125
	v_mul_f32_e32 v122, v122, v123
	v_add_f32_e32 v123, 1.0, v124
	v_rcp_f32_e32 v123, v123
	v_add_f32_e32 v124, 1.0, v125
	v_rcp_f32_e32 v124, v124
	v_cvt_pk_bf16_f32 v121, v121, v122
	v_mul_f32_e32 v116, v116, v123
	v_mul_f32_e32 v112, v116, v112
	v_mul_f32_e32 v116, v117, v124
	v_mul_f32_e32 v117, 0xbfb8aa3b, v118
	v_exp_f32_e32 v117, v117
	v_mul_f32_e32 v122, 0xbfb8aa3b, v119
	v_exp_f32_e32 v122, v122
	v_mul_f32_e32 v113, v116, v113
	v_add_f32_e32 v116, 1.0, v117
	v_rcp_f32_e32 v116, v116
	v_add_f32_e32 v117, 1.0, v122
	v_rcp_f32_e32 v117, v117
	v_cvt_pk_bf16_f32 v122, v112, v113
	v_mul_f32_e32 v112, v118, v116
	v_mul_f32_e32 v118, 0xbfb8aa3b, v108
	v_mul_f32_e32 v113, v119, v117
	v_exp_f32_e32 v118, v118
	v_mul_f32_e32 v119, 0xbfb8aa3b, v109
	v_exp_f32_e32 v119, v119
	v_mul_f32_e32 v112, v112, v114
	v_add_f32_e32 v118, 1.0, v118
	v_rcp_f32_e32 v118, v118
	v_add_f32_e32 v119, 1.0, v119
	v_rcp_f32_e32 v119, v119
	v_mul_f32_e32 v113, v113, v115
	v_cvt_pk_bf16_f32 v123, v112, v113
	v_mov_b64_e32 v[112:113], s[82:83]
	v_mad_i64_i32 v[116:117], s[16:17], v150, s40, v[112:113]
	v_lshlrev_b64 v[114:115], 1, v[152:153]
	v_mul_f32_e32 v108, v108, v118
	v_lshl_add_u64 v[116:117], v[116:117], 0, v[114:115]
	v_mul_f32_e32 v104, v108, v104
	v_mul_f32_e32 v108, v109, v119
	v_mul_f32_e32 v109, 0xbfb8aa3b, v110
	global_store_dwordx4 v[116:117], v[120:123], off
	v_exp_f32_e32 v109, v109
	v_mul_f32_e32 v116, 0xbfb8aa3b, v111
	v_exp_f32_e32 v116, v116
	v_mul_f32_e32 v105, v108, v105
	v_add_f32_e32 v108, 1.0, v109
	v_rcp_f32_e32 v108, v108
	v_add_f32_e32 v109, 1.0, v116
	v_rcp_f32_e32 v109, v109
	v_cvt_pk_bf16_f32 v104, v104, v105
	v_mul_f32_e32 v105, v110, v108
	v_mul_f32_e32 v108, 0xbfb8aa3b, v100
	v_mul_f32_e32 v105, v105, v106
	v_mul_f32_e32 v106, v111, v109
	v_exp_f32_e32 v108, v108
	v_mul_f32_e32 v109, 0xbfb8aa3b, v101
	v_exp_f32_e32 v109, v109
	v_mul_f32_e32 v106, v106, v107
	v_add_f32_e32 v107, 1.0, v108
	v_rcp_f32_e32 v107, v107
	v_add_f32_e32 v108, 1.0, v109
	v_rcp_f32_e32 v108, v108
	v_cvt_pk_bf16_f32 v105, v105, v106
	v_mul_f32_e32 v100, v100, v107
	v_mul_f32_e32 v96, v100, v96
	v_mul_f32_e32 v100, v101, v108
	v_mul_f32_e32 v101, 0xbfb8aa3b, v102
	v_exp_f32_e32 v101, v101
	v_mul_f32_e32 v106, 0xbfb8aa3b, v103
	v_exp_f32_e32 v106, v106
	v_mul_f32_e32 v97, v100, v97
	v_add_f32_e32 v100, 1.0, v101
	v_rcp_f32_e32 v100, v100
	v_add_f32_e32 v101, 1.0, v106
	v_rcp_f32_e32 v101, v101
	v_cvt_pk_bf16_f32 v106, v96, v97
	v_mul_f32_e32 v96, v102, v100
	v_mul_f32_e32 v96, v96, v98
	v_mul_f32_e32 v97, v103, v101
	v_mul_f32_e32 v98, 0xbfb8aa3b, v92
	v_mul_f32_e32 v97, v97, v99
	v_exp_f32_e32 v98, v98
	v_mul_f32_e32 v99, 0xbfb8aa3b, v93
	v_exp_f32_e32 v99, v99
	v_cvt_pk_bf16_f32 v107, v96, v97
	v_add_f32_e32 v98, 1.0, v98
	v_rcp_f32_e32 v98, v98
	v_add_f32_e32 v99, 1.0, v99
	v_rcp_f32_e32 v99, v99
	v_add_u32_e32 v96, 16, v150
	v_mad_i64_i32 v[96:97], s[16:17], v96, s40, v[112:113]
	v_mul_f32_e32 v92, v92, v98
	v_lshl_add_u64 v[96:97], v[96:97], 0, v[114:115]
	v_mul_f32_e32 v88, v92, v88
	v_mul_f32_e32 v92, v93, v99
	v_mul_f32_e32 v93, 0xbfb8aa3b, v94
	global_store_dwordx4 v[96:97], v[104:107], off
	v_exp_f32_e32 v93, v93
	v_mul_f32_e32 v96, 0xbfb8aa3b, v95
	v_exp_f32_e32 v96, v96
	v_mul_f32_e32 v89, v92, v89
	v_add_f32_e32 v92, 1.0, v93
	v_rcp_f32_e32 v92, v92
	v_add_f32_e32 v93, 1.0, v96
	v_rcp_f32_e32 v93, v93
	v_cvt_pk_bf16_f32 v88, v88, v89
	v_mul_f32_e32 v89, v94, v92
	v_mul_f32_e32 v92, 0xbfb8aa3b, v84
	v_mul_f32_e32 v89, v89, v90
	v_mul_f32_e32 v90, v95, v93
	v_exp_f32_e32 v92, v92
	v_mul_f32_e32 v93, 0xbfb8aa3b, v85
	v_exp_f32_e32 v93, v93
	v_mul_f32_e32 v90, v90, v91
	v_add_f32_e32 v91, 1.0, v92
	v_rcp_f32_e32 v91, v91
	v_add_f32_e32 v92, 1.0, v93
	v_rcp_f32_e32 v92, v92
	v_cvt_pk_bf16_f32 v89, v89, v90
	v_mul_f32_e32 v84, v84, v91
	v_mul_f32_e32 v80, v84, v80
	v_mul_f32_e32 v84, v85, v92
	v_mul_f32_e32 v85, 0xbfb8aa3b, v86
	v_exp_f32_e32 v85, v85
	v_mul_f32_e32 v90, 0xbfb8aa3b, v87
	v_exp_f32_e32 v90, v90
	v_mul_f32_e32 v81, v84, v81
	v_add_f32_e32 v84, 1.0, v85
	v_rcp_f32_e32 v84, v84
	v_add_f32_e32 v85, 1.0, v90
	v_rcp_f32_e32 v85, v85
	v_cvt_pk_bf16_f32 v90, v80, v81
	v_mul_f32_e32 v80, v86, v84
	v_mul_f32_e32 v80, v80, v82
	v_mul_f32_e32 v81, v87, v85
	v_mul_f32_e32 v82, 0xbfb8aa3b, v76
	v_mul_f32_e32 v81, v81, v83
	v_exp_f32_e32 v82, v82
	v_mul_f32_e32 v83, 0xbfb8aa3b, v77
	v_exp_f32_e32 v83, v83
	v_cvt_pk_bf16_f32 v91, v80, v81
	v_add_f32_e32 v82, 1.0, v82
	v_rcp_f32_e32 v82, v82
	v_add_f32_e32 v83, 1.0, v83
; __device__ __forceinline__ unsigned cvt_pk_bf16(float lo, float hi) { unsigned r; asm volatile("v_cvt_pk_bf16_f32 %0, %1, %2" : "=v"(r) : "v"(lo), "v"(hi)); return r; }
; __device__ __forceinline__ float silu_f(float a) { return a * __builtin_amdgcn_rcpf(1.0f + __expf(-a)); }
;     __device__ __forceinline__ void operator()(const AccT& acc, const Unit& u, int wr, int wc, int fr, int fq) const {
;     ...
;                 const f32x4 a0 = acc[ai][0][m][0], a1 = acc[ai][0][m][1], b0 = acc[ai][1][m][0], b1 = acc[ai][1][m][1];
;                 u32x4 w;
;                 w.x = cvt_pk_bf16(silu_f(a0[0]) * b0[0], silu_f(a0[1]) * b0[1]); w.y = cvt_pk_bf16(silu_f(a0[2]) * b0[2], silu_f(a0[3]) * b0[3]);
;                 w.z = cvt_pk_bf16(silu_f(a1[0]) * b1[0], silu_f(a1[1]) * b1[1]); w.w = cvt_pk_bf16(silu_f(a1[2]) * b1[2], silu_f(a1[3]) * b1[3]);
;                 *(u32x4*)(H + (size_t)(row0 + ai * 128 + m * 16) * DFF + hc0) = w;
	v_rcp_f32_e32 v83, v83
	v_add_u32_e32 v80, 32, v150
	v_mad_i64_i32 v[80:81], s[16:17], v80, s40, v[112:113]
	v_mul_f32_e32 v76, v76, v82
	v_lshl_add_u64 v[80:81], v[80:81], 0, v[114:115]
	v_mul_f32_e32 v72, v76, v72
	v_mul_f32_e32 v76, v77, v83
	v_mul_f32_e32 v77, 0xbfb8aa3b, v78
	global_store_dwordx4 v[80:81], v[88:91], off
	v_exp_f32_e32 v77, v77
	v_mul_f32_e32 v80, 0xbfb8aa3b, v79
	v_exp_f32_e32 v80, v80
	v_mul_f32_e32 v73, v76, v73
	v_add_f32_e32 v76, 1.0, v77
	v_rcp_f32_e32 v76, v76
	v_add_f32_e32 v77, 1.0, v80
	v_rcp_f32_e32 v77, v77
	v_cvt_pk_bf16_f32 v72, v72, v73
	v_mul_f32_e32 v73, v78, v76
	v_mul_f32_e32 v76, 0xbfb8aa3b, v68
	v_mul_f32_e32 v73, v73, v74
	v_mul_f32_e32 v74, v79, v77
	v_exp_f32_e32 v76, v76
	v_mul_f32_e32 v77, 0xbfb8aa3b, v69
	v_exp_f32_e32 v77, v77
	v_mul_f32_e32 v74, v74, v75
	v_add_f32_e32 v75, 1.0, v76
	v_rcp_f32_e32 v75, v75
	v_add_f32_e32 v76, 1.0, v77
	v_rcp_f32_e32 v76, v76
	v_cvt_pk_bf16_f32 v73, v73, v74
	v_mul_f32_e32 v68, v68, v75
	v_mul_f32_e32 v64, v68, v64
	v_mul_f32_e32 v68, v69, v76
	v_mul_f32_e32 v69, 0xbfb8aa3b, v70
	v_exp_f32_e32 v69, v69
	v_mul_f32_e32 v74, 0xbfb8aa3b, v71
	v_exp_f32_e32 v74, v74
	v_mul_f32_e32 v65, v68, v65
	v_add_f32_e32 v68, 1.0, v69
	v_rcp_f32_e32 v68, v68
	v_add_f32_e32 v69, 1.0, v74
	v_rcp_f32_e32 v69, v69
	v_cvt_pk_bf16_f32 v74, v64, v65
	v_mul_f32_e32 v64, v70, v68
	v_mul_f32_e32 v64, v64, v66
	v_mul_f32_e32 v65, v71, v69
	v_mul_f32_e32 v66, 0xbfb8aa3b, v60
	v_mul_f32_e32 v65, v65, v67
	v_exp_f32_e32 v66, v66
	v_mul_f32_e32 v67, 0xbfb8aa3b, v61
	v_cvt_pk_bf16_f32 v75, v64, v65
	v_add_u32_e32 v64, 48, v150
	v_exp_f32_e32 v67, v67
	v_mad_i64_i32 v[64:65], s[16:17], v64, s40, v[112:113]
	v_lshl_add_u64 v[64:65], v[64:65], 0, v[114:115]
	global_store_dwordx4 v[64:65], v[72:75], off
	v_add_f32_e32 v64, 1.0, v66
	v_rcp_f32_e32 v64, v64
	v_add_f32_e32 v65, 1.0, v67
	v_rcp_f32_e32 v65, v65
	v_add_u32_e32 v66, 0x80, v150
	v_mul_f32_e32 v60, v60, v64
	v_mul_f32_e32 v52, v60, v52
	v_mul_f32_e32 v60, v61, v65
	v_mul_f32_e32 v61, 0xbfb8aa3b, v62
	v_exp_f32_e32 v61, v61
	v_mul_f32_e32 v64, 0xbfb8aa3b, v63
	v_exp_f32_e32 v64, v64
	v_mul_f32_e32 v53, v60, v53
	v_add_f32_e32 v60, 1.0, v61
	v_rcp_f32_e32 v60, v60
	v_add_f32_e32 v61, 1.0, v64
	v_rcp_f32_e32 v61, v61
	v_cvt_pk_bf16_f32 v52, v52, v53
	v_mul_f32_e32 v53, v62, v60
	v_mul_f32_e32 v60, 0xbfb8aa3b, v56
	v_exp_f32_e32 v60, v60
	v_mul_f32_e32 v53, v53, v54
	v_mul_f32_e32 v54, v63, v61
	v_mul_f32_e32 v61, 0xbfb8aa3b, v57
	v_exp_f32_e32 v61, v61
	v_mul_f32_e32 v54, v54, v55
	v_add_f32_e32 v55, 1.0, v60
	v_rcp_f32_e32 v55, v55
	v_add_f32_e32 v60, 1.0, v61
	v_rcp_f32_e32 v60, v60
	v_cvt_pk_bf16_f32 v53, v53, v54
	v_mul_f32_e32 v54, v56, v55
	v_mul_f32_e32 v55, 0xbfb8aa3b, v58
	v_exp_f32_e32 v55, v55
	v_mul_f32_e32 v56, 0xbfb8aa3b, v59
	v_exp_f32_e32 v56, v56
	v_mul_f32_e32 v48, v54, v48
	v_mul_f32_e32 v54, v57, v60
	v_mul_f32_e32 v49, v54, v49
	v_add_f32_e32 v54, 1.0, v55
	v_rcp_f32_e32 v55, v54
	v_add_f32_e32 v54, 1.0, v56
	v_rcp_f32_e32 v56, v54
	v_cvt_pk_bf16_f32 v54, v48, v49
	v_mul_f32_e32 v48, v58, v55
	v_mul_f32_e32 v48, v48, v50
	v_mul_f32_e32 v49, v59, v56
	v_mul_f32_e32 v50, 0xbfb8aa3b, v44
	v_mul_f32_e32 v49, v49, v51
	v_exp_f32_e32 v50, v50
	v_mul_f32_e32 v51, 0xbfb8aa3b, v45
	v_exp_f32_e32 v51, v51
	v_cvt_pk_bf16_f32 v55, v48, v49
	v_add_f32_e32 v50, 1.0, v50
	v_rcp_f32_e32 v50, v50
	v_add_f32_e32 v51, 1.0, v51
	v_rcp_f32_e32 v51, v51
	v_mad_i64_i32 v[48:49], s[16:17], v66, s40, v[112:113]
	v_mul_f32_e32 v44, v44, v50
	v_mul_f32_e32 v36, v44, v36
	v_mul_f32_e32 v44, v45, v51
	v_mul_f32_e32 v45, 0xbfb8aa3b, v46
	v_exp_f32_e32 v45, v45
	v_lshl_add_u64 v[48:49], v[48:49], 0, v[114:115]
	global_store_dwordx4 v[48:49], v[52:55], off
	v_mul_f32_e32 v48, 0xbfb8aa3b, v47
	v_exp_f32_e32 v48, v48
	v_mul_f32_e32 v37, v44, v37
	v_add_f32_e32 v44, 1.0, v45
	v_rcp_f32_e32 v44, v44
	v_add_f32_e32 v45, 1.0, v48
	v_rcp_f32_e32 v45, v45
	v_cvt_pk_bf16_f32 v36, v36, v37
	v_mul_f32_e32 v37, v46, v44
	v_mul_f32_e32 v44, 0xbfb8aa3b, v40
	v_exp_f32_e32 v44, v44
	v_mul_f32_e32 v37, v37, v38
	v_mul_f32_e32 v38, v47, v45
	v_mul_f32_e32 v45, 0xbfb8aa3b, v41
	v_exp_f32_e32 v45, v45
	v_mul_f32_e32 v38, v38, v39
	v_add_f32_e32 v39, 1.0, v44
	v_rcp_f32_e32 v39, v39
; __device__ __forceinline__ unsigned cvt_pk_bf16(float lo, float hi) { unsigned r; asm volatile("v_cvt_pk_bf16_f32 %0, %1, %2" : "=v"(r) : "v"(lo), "v"(hi)); return r; }
; __device__ __forceinline__ float silu_f(float a) { return a * __builtin_amdgcn_rcpf(1.0f + __expf(-a)); }
; template <class Epi, class Sched>
; __device__ __forceinline__ void gemm_phase(LAS unsigned char* lds, const Gemm g, const Sched& S, const Epi& E) {
;     ...
;         cur = nxt; cA = nA; cB = nB; ++ui;
;     __device__ __forceinline__ void operator()(const AccT& acc, const Unit& u, int wr, int wc, int fr, int fq) const {
;     ...
;                 const f32x4 a0 = acc[ai][0][m][0], a1 = acc[ai][0][m][1], b0 = acc[ai][1][m][0], b1 = acc[ai][1][m][1];
;                 u32x4 w;
;                 w.x = cvt_pk_bf16(silu_f(a0[0]) * b0[0], silu_f(a0[1]) * b0[1]); w.y = cvt_pk_bf16(silu_f(a0[2]) * b0[2], silu_f(a0[3]) * b0[3]);
;                 w.z = cvt_pk_bf16(silu_f(a1[0]) * b1[0], silu_f(a1[1]) * b1[1]); w.w = cvt_pk_bf16(silu_f(a1[2]) * b1[2], silu_f(a1[3]) * b1[3]);
;                 *(u32x4*)(H + (size_t)(row0 + ai * 128 + m * 16) * DFF + hc0) = w;
	v_add_f32_e32 v44, 1.0, v45
	v_rcp_f32_e32 v44, v44
	v_cvt_pk_bf16_f32 v37, v37, v38
	v_mul_f32_e32 v38, v40, v39
	v_mul_f32_e32 v39, 0xbfb8aa3b, v42
	v_exp_f32_e32 v39, v39
	v_mul_f32_e32 v40, 0xbfb8aa3b, v43
	v_exp_f32_e32 v40, v40
	v_mul_f32_e32 v32, v38, v32
	v_mul_f32_e32 v38, v41, v44
	v_mul_f32_e32 v33, v38, v33
	v_add_f32_e32 v38, 1.0, v39
	v_rcp_f32_e32 v39, v38
	v_add_f32_e32 v38, 1.0, v40
	v_rcp_f32_e32 v40, v38
	v_cvt_pk_bf16_f32 v38, v32, v33
	v_mul_f32_e32 v32, v42, v39
	v_mul_f32_e32 v32, v32, v34
	v_mul_f32_e32 v33, v43, v40
	v_mul_f32_e32 v34, 0xbfb8aa3b, v28
	v_mul_f32_e32 v33, v33, v35
	v_exp_f32_e32 v34, v34
	v_mul_f32_e32 v35, 0xbfb8aa3b, v29
	v_exp_f32_e32 v35, v35
	v_cvt_pk_bf16_f32 v39, v32, v33
	v_add_f32_e32 v34, 1.0, v34
	v_rcp_f32_e32 v34, v34
	v_add_f32_e32 v35, 1.0, v35
	v_rcp_f32_e32 v35, v35
	v_add_u32_e32 v32, 0x90, v150
	v_mul_f32_e32 v28, v28, v34
	v_mul_f32_e32 v20, v28, v20
	v_mul_f32_e32 v28, v29, v35
	v_mul_f32_e32 v29, 0xbfb8aa3b, v30
	v_exp_f32_e32 v29, v29
	v_mad_i64_i32 v[32:33], s[16:17], v32, s40, v[112:113]
	v_lshl_add_u64 v[32:33], v[32:33], 0, v[114:115]
	global_store_dwordx4 v[32:33], v[36:39], off
	v_mul_f32_e32 v32, 0xbfb8aa3b, v31
	v_exp_f32_e32 v32, v32
	v_mul_f32_e32 v21, v28, v21
	v_add_f32_e32 v28, 1.0, v29
	v_rcp_f32_e32 v28, v28
	v_add_f32_e32 v29, 1.0, v32
	v_rcp_f32_e32 v29, v29
	v_cvt_pk_bf16_f32 v20, v20, v21
	v_mul_f32_e32 v21, v30, v28
	v_mul_f32_e32 v28, 0xbfb8aa3b, v24
	v_exp_f32_e32 v28, v28
	v_mul_f32_e32 v21, v21, v22
	v_mul_f32_e32 v22, v31, v29
	v_mul_f32_e32 v29, 0xbfb8aa3b, v25
	v_exp_f32_e32 v29, v29
	v_mul_f32_e32 v22, v22, v23
	v_add_f32_e32 v23, 1.0, v28
	v_rcp_f32_e32 v23, v23
	v_add_f32_e32 v28, 1.0, v29
	v_rcp_f32_e32 v28, v28
	v_cvt_pk_bf16_f32 v21, v21, v22
	v_mul_f32_e32 v22, v24, v23
	v_mul_f32_e32 v23, 0xbfb8aa3b, v26
	v_exp_f32_e32 v23, v23
	v_mul_f32_e32 v24, 0xbfb8aa3b, v27
	v_exp_f32_e32 v24, v24
	v_mul_f32_e32 v16, v22, v16
	v_mul_f32_e32 v22, v25, v28
	v_mul_f32_e32 v17, v22, v17
	v_add_f32_e32 v22, 1.0, v23
	v_rcp_f32_e32 v23, v22
	v_add_f32_e32 v22, 1.0, v24
	v_rcp_f32_e32 v24, v22
	v_cvt_pk_bf16_f32 v22, v16, v17
	v_mul_f32_e32 v16, v26, v23
	v_mul_f32_e32 v16, v16, v18
	v_mul_f32_e32 v17, v27, v24
	v_mul_f32_e32 v18, 0xbfb8aa3b, v12
	v_mul_f32_e32 v17, v17, v19
	v_exp_f32_e32 v18, v18
	v_mul_f32_e32 v19, 0xbfb8aa3b, v13
	v_exp_f32_e32 v19, v19
	v_cvt_pk_bf16_f32 v23, v16, v17
	v_add_f32_e32 v18, 1.0, v18
	v_rcp_f32_e32 v18, v18
	v_add_f32_e32 v19, 1.0, v19
	v_rcp_f32_e32 v19, v19
	v_add_u32_e32 v16, 0xa0, v150
	v_mul_f32_e32 v12, v12, v18
	v_mul_f32_e32 v4, v12, v4
	v_mul_f32_e32 v12, v13, v19
	v_mul_f32_e32 v13, 0xbfb8aa3b, v14
	v_exp_f32_e32 v13, v13
	v_mad_i64_i32 v[16:17], s[16:17], v16, s40, v[112:113]
	v_lshl_add_u64 v[16:17], v[16:17], 0, v[114:115]
	global_store_dwordx4 v[16:17], v[20:23], off
	v_mul_f32_e32 v16, 0xbfb8aa3b, v15
	v_exp_f32_e32 v16, v16
	v_mul_f32_e32 v5, v12, v5
	v_add_f32_e32 v12, 1.0, v13
	v_rcp_f32_e32 v12, v12
	v_add_f32_e32 v13, 1.0, v16
	v_rcp_f32_e32 v13, v13
	v_cvt_pk_bf16_f32 v4, v4, v5
	v_mul_f32_e32 v5, v14, v12
	v_mul_f32_e32 v12, 0xbfb8aa3b, v8
	v_exp_f32_e32 v12, v12
	v_mul_f32_e32 v5, v5, v6
	v_mul_f32_e32 v6, v15, v13
	v_mul_f32_e32 v13, 0xbfb8aa3b, v9
	v_exp_f32_e32 v13, v13
	v_mul_f32_e32 v6, v6, v7
	v_add_f32_e32 v7, 1.0, v12
	v_rcp_f32_e32 v7, v7
	v_add_f32_e32 v12, 1.0, v13
	v_rcp_f32_e32 v12, v12
	v_cvt_pk_bf16_f32 v5, v5, v6
	v_mul_f32_e32 v6, v8, v7
	v_mul_f32_e32 v7, 0xbfb8aa3b, v10
	v_exp_f32_e32 v7, v7
	v_mul_f32_e32 v8, 0xbfb8aa3b, v11
	v_exp_f32_e32 v8, v8
	v_mul_f32_e32 v0, v6, v0
	v_mul_f32_e32 v6, v9, v12
	v_mul_f32_e32 v1, v6, v1
	v_add_f32_e32 v6, 1.0, v7
	v_rcp_f32_e32 v7, v6
	v_add_f32_e32 v6, 1.0, v8
	v_rcp_f32_e32 v8, v6
	v_cvt_pk_bf16_f32 v6, v0, v1
	v_mul_f32_e32 v0, v10, v7
	v_mul_f32_e32 v0, v0, v2
	v_mul_f32_e32 v1, v11, v8
	v_mul_f32_e32 v1, v1, v3
	v_cvt_pk_bf16_f32 v7, v0, v1
	v_add_u32_e32 v0, 0xb0, v150
	v_mad_i64_i32 v[0:1], s[16:17], v0, s40, v[112:113]
	v_lshl_add_u64 v[0:1], v[0:1], 0, v[114:115]
	s_and_b64 vcc, exec, s[2:3]
	s_mov_b32 s41, s4
	s_mov_b32 s14, s6
	s_mov_b64 s[18:19], s[12:13]
	s_mov_b64 s[16:17], s[10:11]
	global_store_dwordx4 v[0:1], v[4:7], off
	s_barrier
	s_cbranch_vccz .LBB0_1018
